# P5 K-loop head: spurious s_waitcnt vmcnt(0) (compiler WAW guard on a path that cannot occur) replaced by s_nop 0
# speedup vs baseline: 1.0094x; 1.0012x over previous
; #define LAS __attribute__((address_space(3)))
; __device__ __forceinline__ void mixer_b_unit(const Args& a, LAS unsigned char* lds, int unit) {
;     ...
;     const int q = unit & 3, hd = (unit >> 2) & 15, b = unit >> 6;
;     const int HC = hd * LHD, OC = HC + 64 * q;
;     const bf16* XR = (const bf16*)(ws + WS_XR); const bf16* GYR = (const bf16*)(ws + WS_GYR); bf16* YB = (bf16*)(ws + WS_YB);
;     const bf16* WaT = (const bf16*)(ws + WS_WA) + (size_t)hd * LHD * LHD; const bf16* WxT = (const bf16*)(ws + WS_WX) + (size_t)hd * LHD * LHD;
;     const int fr = lane & 15, fq = lane >> 4, cb = wave & 3, rh = wave >> 2;
;     bf16x8 bfa[8];
; #pragma unroll
;     for (int ks = 0; ks < 8; ++ks) { const size_t o = (size_t)(64 * q + 16 * cb + fr) * LHD + 32 * ks + 8 * fq; bfa[ks] = *(const bf16x8*)(WaT + o); }
;     { const int wrw = tid >> 3, wch = tid & 7;
; #pragma unroll
;       for (int i = 0; i < 4; ++i) *(LAS u32x4*)(lds + MB_WX + wrw * MB_XPITCH + (wch * 4 + i) * 16) = *(const u32x4*)(WxT + (size_t)(64 * q + wrw) * LHD + (wch * 4 + i) * 8); }
;     f32x2 ba2[2], bx2[2], spl2[2], spy2[2];
; #pragma unroll
;     for (int e = 0; e < 4; ++e) { const int col = OC + 16 * cb + 4 * fq + e; const float sp = -8.0f * log1pf(expf(-a.in[13][col]));
;         ba2[e >> 1][e & 1] = -1.4426950409f * a.in[10][col]; bx2[e >> 1][e & 1] = -1.4426950409f * a.in[12][col]; spl2[e >> 1][e & 1] = 1.4426950409f * sp; spy2[e >> 1][e & 1] = 2.0f * sp; }
.LBB0_623:
	s_or_b64 exec, exec, s[2:3]
	s_waitcnt vmcnt(2)
	v_mul_f32_e32 v4, 0xbfb8aa3b, v74
	v_rndne_f32_e32 v5, v4
	v_sub_f32_e32 v86, v4, v5
	v_fma_f32 v4, v74, s20, -v4
	v_fmac_f32_e32 v4, 0xb2a5705f, v74
	v_add_f32_e32 v4, v86, v4
	s_mul_i32 s0, s12, 0x1980
	s_bfe_u32 s1, s42, 0x30005
	v_exp_f32_e32 v4, v4
	v_cvt_i32_f32_e32 v5, v5
	s_add_i32 s4, s0, 0
	s_lshr_b32 s0, s42, 5
	s_lshl_b32 s3, s1, 13
	s_and_b32 s5, s16, 31
	s_lshl_b32 s8, s1, 14
	s_lshl_b32 s1, s42, 17
	s_and_b32 s2, s1, 0x1800000
	s_lshl_b32 s1, s5, 6
	s_lshl_b32 s0, s0, 11
	s_or_b32 s0, s0, s1
	s_mov_b32 s1, 0x42ce8ed0
	s_lshl_b32 s9, s5, 8
	s_lshl_b32 s10, s5, 9
	v_ldexp_f32 v4, v4, v5
	v_cmp_nlt_f32_e32 vcc, s1, v74
	s_mov_b32 s5, 0xc2b17218
	s_mov_b32 s6, 0x3f2aaaab
	v_cndmask_b32_e32 v4, 0, v4, vcc
	v_cmp_ngt_f32_e32 vcc, s5, v74
	s_waitcnt vmcnt(0)
	v_pk_mul_f32 v[124:125], v[70:71], s[20:21] op_sel_hi:[1,0]
	s_and_b32 s11, s0, 0xf00
	v_cndmask_b32_e32 v110, v139, v4, vcc
	v_add_f32_e32 v74, 1.0, v110
	v_add_f32_e32 v4, -1.0, v74
	v_sub_f32_e32 v5, v4, v74
	v_add_f32_e32 v5, 1.0, v5
	v_sub_f32_e32 v4, v110, v4
	v_add_f32_e32 v86, v4, v5
	v_mul_f32_e32 v4, 0xbfb8aa3b, v75
	v_rndne_f32_e32 v5, v4
	v_sub_f32_e32 v87, v4, v5
	v_fma_f32 v4, v75, s20, -v4
	v_fmac_f32_e32 v4, 0xb2a5705f, v75
	v_add_f32_e32 v4, v87, v4
	v_exp_f32_e32 v87, v4
	v_cvt_i32_f32_e32 v88, v5
	v_cvt_f64_f32_e32 v[4:5], v74
	v_frexp_exp_i32_f64_e32 v90, v[4:5]
	v_cmp_nlt_f32_e32 vcc, s1, v75
	v_ldexp_f32 v4, v87, v88
	v_frexp_mant_f32_e32 v89, v74
	v_cndmask_b32_e32 v4, 0, v4, vcc
	v_cmp_ngt_f32_e32 vcc, s5, v75
	s_mov_b32 s0, 0x3ecc95a3
	s_mov_b32 s18, 0x3e9b6dac
	v_cndmask_b32_e32 v111, v139, v4, vcc
	v_add_f32_e32 v75, 1.0, v111
	v_add_f32_e32 v4, -1.0, v75
	v_sub_f32_e32 v5, v4, v75
	v_add_f32_e32 v5, 1.0, v5
	v_sub_f32_e32 v4, v111, v4
	v_add_f32_e32 v87, v4, v5
	v_frexp_mant_f32_e32 v88, v75
	v_cvt_f64_f32_e32 v[4:5], v75
	v_frexp_exp_i32_f64_e32 v91, v[4:5]
	v_cmp_gt_f32_e32 vcc, s6, v88
	v_pk_mul_f32 v[4:5], v[66:67], s[20:21] op_sel_hi:[1,0]
	s_mov_b32 s24, 0x3f2aaada
	v_subbrev_co_u32_e32 v100, vcc, 0, v91, vcc
	v_cmp_gt_f32_e32 vcc, s6, v89
	v_sub_u32_e32 v71, 0, v100
	s_mov_b32 s28, 0x3f317218
	v_subbrev_co_u32_e32 v101, vcc, 0, v90, vcc
	v_sub_u32_e32 v67, 0, v101
	v_ldexp_f32 v66, v74, v67
	v_ldexp_f32 v70, v86, v67
	v_ldexp_f32 v67, v75, v71
	v_pk_add_f32 v[74:75], v[66:67], 1.0 op_sel_hi:[1,0]
	v_ldexp_f32 v71, v87, v71
	v_pk_add_f32 v[86:87], v[74:75], -1.0 op_sel_hi:[1,0]
	v_pk_add_f32 v[92:93], v[66:67], -1.0 op_sel_hi:[1,0]
	v_pk_add_f32 v[86:87], v[66:67], v[86:87] neg_lo:[0,1] neg_hi:[0,1]
	v_pk_add_f32 v[94:95], v[92:93], 1.0 op_sel_hi:[1,0]
	v_pk_add_f32 v[86:87], v[70:71], v[86:87]
	v_pk_add_f32 v[66:67], v[66:67], v[94:95] neg_lo:[0,1] neg_hi:[0,1]
	v_pk_add_f32 v[88:89], v[74:75], v[86:87]
	v_pk_add_f32 v[66:67], v[70:71], v[66:67]
	v_rcp_f32_e32 v90, v88
	v_rcp_f32_e32 v91, v89
	v_pk_add_f32 v[70:71], v[92:93], v[66:67]
	v_pk_add_f32 v[74:75], v[74:75], v[88:89] neg_lo:[0,1] neg_hi:[0,1]
	v_pk_add_f32 v[92:93], v[92:93], v[70:71] neg_lo:[0,1] neg_hi:[0,1]
	v_pk_add_f32 v[74:75], v[86:87], v[74:75]
	v_pk_mul_f32 v[86:87], v[70:71], v[90:91]
	v_pk_add_f32 v[66:67], v[66:67], v[92:93]
	v_pk_mul_f32 v[92:93], v[88:89], v[86:87]
	s_mov_b32 s30, 0xb102e308
	v_pk_fma_f32 v[94:95], v[86:87], v[88:89], v[92:93] neg_lo:[0,0,1] neg_hi:[0,0,1]
	s_mov_b32 s7, 0x33800000
	v_pk_fma_f32 v[94:95], v[86:87], v[74:75], v[94:95]
	s_mov_b32 s34, 0xc1000000
	v_pk_add_f32 v[96:97], v[92:93], v[94:95]
	v_pk_mul_f32 v[130:131], v[68:69], s[20:21] op_sel_hi:[1,0]
	v_pk_add_f32 v[98:99], v[70:71], v[96:97] neg_lo:[0,1] neg_hi:[0,1]
	v_pk_add_f32 v[92:93], v[96:97], v[92:93] neg_lo:[0,1] neg_hi:[0,1]
	v_pk_add_f32 v[70:71], v[70:71], v[98:99] neg_lo:[0,1] neg_hi:[0,1]
	v_pk_mul_f32 v[132:133], v[72:73], s[20:21] op_sel_hi:[1,0]
	v_pk_add_f32 v[70:71], v[70:71], v[96:97] neg_lo:[0,1] neg_hi:[0,1]
	v_lshlrev_b32_e32 v81, 3, v79
	v_pk_add_f32 v[66:67], v[66:67], v[70:71]
	v_pk_add_f32 v[70:71], v[92:93], v[94:95] neg_lo:[0,1] neg_hi:[0,1]
	v_and_b32_e32 v2, 63, v78
	v_pk_add_f32 v[66:67], v[70:71], v[66:67]
	s_add_i32 s4, s4, 0x11a00
	v_pk_add_f32 v[70:71], v[98:99], v[66:67]
	v_and_b32_e32 v157, 7, v78
	v_pk_mul_f32 v[92:93], v[90:91], v[70:71]
	v_lshrrev_b32_e32 v159, 2, v2
	v_pk_mul_f32 v[94:95], v[88:89], v[92:93]
	s_and_b32 s16, s16, 3
	v_pk_fma_f32 v[88:89], v[92:93], v[88:89], v[94:95] neg_lo:[0,0,1] neg_hi:[0,0,1]
	s_waitcnt lgkmcnt(0)
; #define LAS __attribute__((address_space(3)))
; #define LDS_WAIT() asm volatile("s_waitcnt lgkmcnt(0)" ::: "memory")
; __device__ __forceinline__ void mixer_b_unit(const Args& a, LAS unsigned char* lds, int unit) {
;     ...
;     for (int e = 0; e < 4; ++e) { const int col = OC + 16 * cb + 4 * fq + e; const float sp = -8.0f * log1pf(expf(-a.in[13][col]));
;         ba2[e >> 1][e & 1] = -1.4426950409f * a.in[10][col]; bx2[e >> 1][e & 1] = -1.4426950409f * a.in[12][col]; spl2[e >> 1][e & 1] = 1.4426950409f * sp; spy2[e >> 1][e & 1] = 2.0f * sp; }
;     const int cg = tid & 31, rg = tid >> 5;
;     LAS float* ctab = (LAS float*)(lds + MB_CTAB);
;     for (int i = tid; i < 5 * LHD; i += NWAVES * 64) { const int k = i >> 8, c = i & 255; ctab[i] = (k < 4) ? a.in[7][(size_t)k * LW + HC + c] : a.in[8][HC + c]; }
;     LAS f32x2* ag = (LAS f32x2*)(lds + MB_AG);
;     LAS unsigned* cscr = (LAS unsigned*)(lds + MB_CVT + wave * (3 * 32 * 17 * 4));
;     const int c8 = lane & 7, rgp = lane >> 3;
;     float carry = 0.f;
;     const bf16* xrp = XR + ((size_t)b * SEQ + 4 * rg) * LW + HC + 8 * cg;
;     u32x4 raw[7];
; #pragma unroll
;     for (int i = 0; i < 7; ++i) raw[i] = (4 * rg - 3 + i >= 0) ? *(const u32x4*)(xrp + (ptrdiff_t)(i - 3) * LW) : (u32x4){0u, 0u, 0u, 0u};
;     const int sidu = (unit * MB_STEPS * NWAVES + wave) * CV_SLOTS;
;     LDS_WAIT(); __syncthreads();
	s_add_i32 s3, s12, s3
	v_pk_fma_f32 v[74:75], v[92:93], v[74:75], v[88:89]
	v_pk_add_f32 v[88:89], v[98:99], v[70:71] neg_lo:[0,1] neg_hi:[0,1]
	s_lshl_b32 s17, s12, 1
	v_pk_add_f32 v[66:67], v[66:67], v[88:89]
	v_pk_add_f32 v[88:89], v[94:95], v[74:75]
	s_add_i32 s48, s3, s9
	v_pk_add_f32 v[96:97], v[70:71], v[88:89] neg_lo:[0,1] neg_hi:[0,1]
	v_pk_add_f32 v[94:95], v[88:89], v[94:95] neg_lo:[0,1] neg_hi:[0,1]
	v_pk_add_f32 v[70:71], v[70:71], v[96:97] neg_lo:[0,1] neg_hi:[0,1]
	s_or_b32 s3, s8, s10
	v_pk_add_f32 v[70:71], v[70:71], v[88:89] neg_lo:[0,1] neg_hi:[0,1]
	v_cvt_f32_i32_e32 v89, v100
	v_pk_add_f32 v[66:67], v[66:67], v[70:71]
	v_pk_add_f32 v[70:71], v[94:95], v[74:75] neg_lo:[0,1] neg_hi:[0,1]
	v_cvt_f32_i32_e32 v88, v101
	v_pk_add_f32 v[66:67], v[70:71], v[66:67]
	v_pk_add_f32 v[70:71], v[86:87], v[92:93]
	v_pk_add_f32 v[66:67], v[96:97], v[66:67]
	v_pk_add_f32 v[74:75], v[70:71], v[86:87] neg_lo:[0,1] neg_hi:[0,1]
	v_pk_mul_f32 v[66:67], v[90:91], v[66:67]
	v_pk_add_f32 v[74:75], v[92:93], v[74:75] neg_lo:[0,1] neg_hi:[0,1]
	v_mov_b64_e32 v[90:91], s[0:1]
	v_pk_add_f32 v[66:67], v[74:75], v[66:67]
	v_pk_mul_f32 v[94:95], v[88:89], s[28:29] op_sel_hi:[1,0]
	v_pk_add_f32 v[74:75], v[70:71], v[66:67]
	v_pk_fma_f32 v[96:97], v[88:89], s[28:29], v[94:95] op_sel_hi:[1,0,1] neg_lo:[0,0,1] neg_hi:[0,0,1]
	v_pk_mul_f32 v[86:87], v[74:75], v[74:75]
	v_pk_add_f32 v[70:71], v[74:75], v[70:71] neg_lo:[0,1] neg_hi:[0,1]
	v_pk_fma_f32 v[92:93], v[86:87], s[18:19], v[90:91] op_sel_hi:[1,0,0]
	v_pk_add_f32 v[66:67], v[66:67], v[70:71] neg_lo:[0,1] neg_hi:[0,1]
	v_ldexp_f32 v70, v74, 1
	v_pk_fma_f32 v[92:93], v[86:87], v[92:93], s[24:25] op_sel_hi:[1,1,0]
	v_ldexp_f32 v71, v75, 1
	v_pk_mul_f32 v[74:75], v[74:75], v[86:87]
	v_ldexp_f32 v99, v67, 1
	v_pk_mul_f32 v[74:75], v[74:75], v[92:93]
	v_ldexp_f32 v66, v66, 1
	v_pk_add_f32 v[86:87], v[70:71], v[74:75]
	v_mov_b32_e32 v67, v99
	v_pk_add_f32 v[70:71], v[86:87], v[70:71] neg_lo:[0,1] neg_hi:[0,1]
	v_pk_fma_f32 v[88:89], v[88:89], s[30:31], v[96:97] op_sel_hi:[1,0,1]
	v_pk_add_f32 v[70:71], v[74:75], v[70:71] neg_lo:[0,1] neg_hi:[0,1]
	v_pk_add_f32 v[96:97], v[94:95], v[88:89]
	v_pk_add_f32 v[92:93], v[66:67], v[70:71]
	v_mov_b32_e32 v75, v71
	v_mov_b32_e32 v67, v93
	v_mov_b32_e32 v71, v87
	v_mov_b32_e32 v74, v94
	v_mov_b32_e32 v98, v88
	v_pk_add_f32 v[66:67], v[66:67], v[70:71]
	v_pk_add_f32 v[70:71], v[86:87], v[92:93]
	v_pk_add_f32 v[74:75], v[74:75], v[98:99]
	v_mov_b32_e32 v98, v96
	v_mov_b32_e32 v99, v95
	v_mov_b32_e32 v100, v70
	v_mov_b32_e32 v101, v89
	v_mov_b32_e32 v104, v96
	v_mov_b32_e32 v105, v87
	v_mov_b32_e32 v106, v70
	v_mov_b32_e32 v107, v93
	v_pk_add_f32 v[102:103], v[98:99], v[100:101]
	v_pk_add_f32 v[104:105], v[104:105], v[106:107]
	v_pk_add_f32 v[106:107], v[96:97], v[70:71]
	v_pk_add_f32 v[98:99], v[102:103], v[98:99] neg_lo:[0,1] neg_hi:[0,1]
	v_mov_b32_e32 v102, v70
	v_mov_b32_e32 v103, v107
	v_mov_b32_e32 v108, v86
	v_mov_b32_e32 v109, v97
	v_pk_add_f32 v[102:103], v[102:103], v[108:109] neg_lo:[0,1] neg_hi:[0,1]
	v_mov_b32_e32 v108, v96
	v_mov_b32_e32 v109, v107
	v_mov_b32_e32 v95, v103
	v_pk_add_f32 v[94:95], v[108:109], v[94:95] neg_lo:[0,1] neg_hi:[0,1]
	v_pk_add_f32 v[100:101], v[100:101], v[98:99] neg_lo:[0,1] neg_hi:[0,1]
	v_mov_b32_e32 v108, v94
	v_mov_b32_e32 v109, v99
	v_mov_b32_e32 v99, v87
	v_pk_add_f32 v[108:109], v[88:89], v[108:109] neg_lo:[0,1] neg_hi:[0,1]
	v_pk_add_f32 v[98:99], v[104:105], v[98:99] neg_lo:[0,1] neg_hi:[0,1]
	v_mov_b32_e32 v89, v97
	v_pk_add_f32 v[70:71], v[70:71], v[86:87] neg_lo:[0,1] neg_hi:[0,1]
	v_pk_add_f32 v[74:75], v[74:75], v[98:99] neg_lo:[0,1] neg_hi:[0,1]
	v_pk_add_f32 v[86:87], v[88:89], v[94:95] neg_lo:[0,1] neg_hi:[0,1]
	v_pk_add_f32 v[66:67], v[66:67], v[102:103] neg_lo:[0,1] neg_hi:[0,1]
	v_pk_add_f32 v[70:71], v[92:93], v[70:71] neg_lo:[0,1] neg_hi:[0,1]
	v_pk_add_f32 v[88:89], v[66:67], v[86:87]
	v_mov_b32_e32 v67, v75
	v_pk_add_f32 v[92:93], v[100:101], v[74:75]
	v_pk_add_f32 v[66:67], v[108:109], v[66:67]
	v_mov_b32_e32 v87, v101
	v_pk_add_f32 v[66:67], v[66:67], v[86:87] neg_lo:[0,1] neg_hi:[0,1]
	v_mov_b32_e32 v74, v88
	v_mov_b32_e32 v75, v93
	v_pk_add_f32 v[74:75], v[74:75], v[66:67] neg_lo:[0,1] neg_hi:[0,1]
	v_pk_add_f32 v[66:67], v[70:71], v[66:67] neg_lo:[0,1] neg_hi:[0,1]
	v_pk_add_f32 v[74:75], v[86:87], v[74:75] neg_lo:[0,1] neg_hi:[0,1]
	v_pk_add_f32 v[70:71], v[92:93], v[88:89]
	v_pk_add_f32 v[66:67], v[66:67], v[74:75]
	v_pk_add_f32 v[74:75], v[106:107], v[70:71]
	s_mov_b32 s0, 0x7f800000
	v_pk_add_f32 v[86:87], v[74:75], v[106:107] neg_lo:[0,1] neg_hi:[0,1]
	v_cmp_neq_f32_e32 vcc, s0, v110
	v_pk_add_f32 v[70:71], v[70:71], v[86:87] neg_lo:[0,1] neg_hi:[0,1]
	v_mov_b32_e32 v156, 0
	v_pk_add_f32 v[66:67], v[66:67], v[70:71]
	v_mul_f32_e32 v70, 0xbfb8aa3b, v76
	v_rndne_f32_e32 v71, v70
	v_pk_add_f32 v[66:67], v[74:75], v[66:67]
	v_sub_f32_e32 v74, v70, v71
	v_fma_f32 v70, v76, s20, -v70
	v_fmac_f32_e32 v70, 0xb2a5705f, v76
	v_cndmask_b32_e32 v66, v139, v66, vcc
	v_cmp_neq_f32_e32 vcc, s0, v111
	v_add_f32_e32 v70, v74, v70
	v_exp_f32_e32 v70, v70
	v_cndmask_b32_e32 v67, v139, v67, vcc
	v_cmp_lt_f32_e64 vcc, |v111|, s7
	v_cvt_i32_f32_e32 v71, v71
	v_and_b32_e32 v138, 14, v159
	v_cndmask_b32_e32 v67, v67, v111, vcc
	v_cmp_lt_f32_e64 vcc, |v110|, s7
	s_mov_b32 s23, s26
	v_or_b32_e32 v160, 16, v159
	v_cndmask_b32_e32 v66, v66, v110, vcc
	v_pk_mul_f32 v[66:67], v[66:67], s[34:35] op_sel_hi:[1,0]
	v_cmp_nlt_f32_e32 vcc, s1, v76
	v_pk_add_f32 v[126:127], v[66:67], v[66:67]
	v_pk_mul_f32 v[128:129], v[66:67], s[74:75] op_sel_hi:[1,0]
	v_ldexp_f32 v66, v70, v71
	v_cndmask_b32_e32 v66, 0, v66, vcc
	v_cmp_ngt_f32_e32 vcc, s5, v76
	s_lshl_b32 s49, s48, 5
	s_add_i32 s50, s3, s17
	v_cndmask_b32_e32 v102, v139, v66, vcc
	v_add_f32_e32 v70, 1.0, v102
	v_add_f32_e32 v66, -1.0, v70
	v_sub_f32_e32 v67, v66, v70
	v_add_f32_e32 v67, 1.0, v67
	v_sub_f32_e32 v66, v102, v66
	v_add_f32_e32 v71, v66, v67
	v_mul_f32_e32 v66, 0xbfb8aa3b, v77
	v_rndne_f32_e32 v67, v66
	v_sub_f32_e32 v74, v66, v67
	v_fma_f32 v66, v77, s20, -v66
	v_fmac_f32_e32 v66, 0xb2a5705f, v77
	v_add_f32_e32 v66, v74, v66
	v_exp_f32_e32 v74, v66
	v_cvt_i32_f32_e32 v75, v67
	v_cvt_f64_f32_e32 v[66:67], v70
	v_frexp_exp_i32_f64_e32 v86, v[66:67]
	v_cmp_nlt_f32_e32 vcc, s1, v77
	v_ldexp_f32 v66, v74, v75
	v_frexp_mant_f32_e32 v76, v70
	v_cndmask_b32_e32 v66, 0, v66, vcc
	v_cmp_ngt_f32_e32 vcc, s5, v77
	s_mov_b64 s[86:87], 0
	s_mov_b32 s51, 61
	v_cndmask_b32_e32 v103, v139, v66, vcc
	v_add_f32_e32 v74, 1.0, v103
	v_add_f32_e32 v66, -1.0, v74
	v_sub_f32_e32 v67, v66, v74
	v_add_f32_e32 v67, 1.0, v67
	v_sub_f32_e32 v66, v103, v66
	v_add_f32_e32 v75, v66, v67
	v_frexp_mant_f32_e32 v77, v74
	v_cvt_f64_f32_e32 v[66:67], v74
	v_frexp_exp_i32_f64_e32 v66, v[66:67]
	v_cmp_gt_f32_e32 vcc, s6, v77
	s_waitcnt lgkmcnt(0)
	s_barrier
; __device__ __forceinline__ void mixer_b_unit(const Args& a, LAS unsigned char* lds, int unit) {
;     ...
;     for (int e = 0; e < 4; ++e) { const int col = OC + 16 * cb + 4 * fq + e; const float sp = -8.0f * log1pf(expf(-a.in[13][col]));
;         ba2[e >> 1][e & 1] = -1.4426950409f * a.in[10][col]; bx2[e >> 1][e & 1] = -1.4426950409f * a.in[12][col]; spl2[e >> 1][e & 1] = 1.4426950409f * sp; spy2[e >> 1][e & 1] = 2.0f * sp; }
	v_subbrev_co_u32_e32 v96, vcc, 0, v66, vcc
	v_cmp_gt_f32_e32 vcc, s6, v76
	v_sub_u32_e32 v69, 0, v96
	s_nop 0
	v_subbrev_co_u32_e32 v97, vcc, 0, v86, vcc
	v_sub_u32_e32 v67, 0, v97
	v_ldexp_f32 v66, v70, v67
	v_ldexp_f32 v68, v71, v67
	v_ldexp_f32 v67, v74, v69
	v_pk_add_f32 v[70:71], v[66:67], 1.0 op_sel_hi:[1,0]
	v_ldexp_f32 v69, v75, v69
	v_pk_add_f32 v[72:73], v[70:71], -1.0 op_sel_hi:[1,0]
	v_pk_add_f32 v[86:87], v[66:67], -1.0 op_sel_hi:[1,0]
	v_pk_add_f32 v[72:73], v[66:67], v[72:73] neg_lo:[0,1] neg_hi:[0,1]
	v_pk_add_f32 v[88:89], v[86:87], 1.0 op_sel_hi:[1,0]
	v_pk_add_f32 v[72:73], v[68:69], v[72:73]
	v_pk_add_f32 v[66:67], v[66:67], v[88:89] neg_lo:[0,1] neg_hi:[0,1]
	v_pk_add_f32 v[74:75], v[70:71], v[72:73]
	v_pk_add_f32 v[66:67], v[68:69], v[66:67]
	v_rcp_f32_e32 v76, v74
	v_rcp_f32_e32 v77, v75
	v_pk_add_f32 v[68:69], v[86:87], v[66:67]
	v_pk_add_f32 v[70:71], v[70:71], v[74:75] neg_lo:[0,1] neg_hi:[0,1]
	v_pk_add_f32 v[86:87], v[86:87], v[68:69] neg_lo:[0,1] neg_hi:[0,1]
	v_pk_add_f32 v[70:71], v[72:73], v[70:71]
	v_pk_mul_f32 v[72:73], v[68:69], v[76:77]
	v_pk_add_f32 v[66:67], v[66:67], v[86:87]
	v_pk_mul_f32 v[86:87], v[74:75], v[72:73]
	v_cmp_neq_f32_e32 vcc, s0, v102
	v_pk_fma_f32 v[88:89], v[72:73], v[74:75], v[86:87] neg_lo:[0,0,1] neg_hi:[0,0,1]
	s_nop 0
	v_pk_fma_f32 v[88:89], v[72:73], v[70:71], v[88:89]
	s_nop 0
	v_pk_add_f32 v[92:93], v[86:87], v[88:89]
	s_nop 0
	v_pk_add_f32 v[94:95], v[68:69], v[92:93] neg_lo:[0,1] neg_hi:[0,1]
	v_pk_add_f32 v[86:87], v[92:93], v[86:87] neg_lo:[0,1] neg_hi:[0,1]
	v_pk_add_f32 v[68:69], v[68:69], v[94:95] neg_lo:[0,1] neg_hi:[0,1]
	s_nop 0
	v_pk_add_f32 v[68:69], v[68:69], v[92:93] neg_lo:[0,1] neg_hi:[0,1]
	s_nop 0
	v_pk_add_f32 v[66:67], v[66:67], v[68:69]
	v_pk_add_f32 v[68:69], v[86:87], v[88:89] neg_lo:[0,1] neg_hi:[0,1]
	s_nop 0
	v_pk_add_f32 v[66:67], v[68:69], v[66:67]
	s_nop 0
	v_pk_add_f32 v[68:69], v[94:95], v[66:67]
	s_nop 0
	v_pk_mul_f32 v[86:87], v[76:77], v[68:69]
	s_nop 0
	v_pk_mul_f32 v[88:89], v[74:75], v[86:87]
	s_nop 0
	v_pk_fma_f32 v[74:75], v[86:87], v[74:75], v[88:89] neg_lo:[0,0,1] neg_hi:[0,0,1]
	s_nop 0
	v_pk_fma_f32 v[70:71], v[86:87], v[70:71], v[74:75]
	v_pk_add_f32 v[74:75], v[94:95], v[68:69] neg_lo:[0,1] neg_hi:[0,1]
	s_nop 0
	v_pk_add_f32 v[66:67], v[66:67], v[74:75]
	v_pk_add_f32 v[74:75], v[88:89], v[70:71]
	s_nop 0
	v_pk_add_f32 v[92:93], v[68:69], v[74:75] neg_lo:[0,1] neg_hi:[0,1]
	v_pk_add_f32 v[88:89], v[74:75], v[88:89] neg_lo:[0,1] neg_hi:[0,1]
	v_pk_add_f32 v[68:69], v[68:69], v[92:93] neg_lo:[0,1] neg_hi:[0,1]
	s_nop 0
	v_pk_add_f32 v[68:69], v[68:69], v[74:75] neg_lo:[0,1] neg_hi:[0,1]
	s_nop 0
	v_pk_add_f32 v[66:67], v[66:67], v[68:69]
	v_pk_add_f32 v[68:69], v[88:89], v[70:71] neg_lo:[0,1] neg_hi:[0,1]
	s_nop 0
	v_pk_add_f32 v[66:67], v[68:69], v[66:67]
	v_pk_add_f32 v[68:69], v[72:73], v[86:87]
	v_pk_add_f32 v[66:67], v[92:93], v[66:67]
	v_pk_add_f32 v[70:71], v[68:69], v[72:73] neg_lo:[0,1] neg_hi:[0,1]
	v_pk_mul_f32 v[66:67], v[76:77], v[66:67]
	v_pk_add_f32 v[70:71], v[86:87], v[70:71] neg_lo:[0,1] neg_hi:[0,1]
	v_cvt_f32_i32_e32 v73, v96
	v_pk_add_f32 v[66:67], v[70:71], v[66:67]
	v_cvt_f32_i32_e32 v72, v97
	v_pk_add_f32 v[70:71], v[68:69], v[66:67]
	v_pk_mul_f32 v[86:87], v[72:73], s[28:29] op_sel_hi:[1,0]
	v_pk_mul_f32 v[74:75], v[70:71], v[70:71]
	v_pk_add_f32 v[68:69], v[70:71], v[68:69] neg_lo:[0,1] neg_hi:[0,1]
	v_pk_fma_f32 v[76:77], v[74:75], s[18:19], v[90:91] op_sel_hi:[1,0,0]
	v_pk_add_f32 v[66:67], v[66:67], v[68:69] neg_lo:[0,1] neg_hi:[0,1]
	v_ldexp_f32 v68, v70, 1
	v_pk_fma_f32 v[76:77], v[74:75], v[76:77], s[24:25] op_sel_hi:[1,1,0]
	v_ldexp_f32 v69, v71, 1
	v_pk_mul_f32 v[70:71], v[70:71], v[74:75]
	v_ldexp_f32 v91, v67, 1
	v_pk_mul_f32 v[70:71], v[70:71], v[76:77]
	v_ldexp_f32 v66, v66, 1
	v_pk_add_f32 v[74:75], v[68:69], v[70:71]
	v_mov_b32_e32 v67, v91
	v_pk_add_f32 v[68:69], v[74:75], v[68:69] neg_lo:[0,1] neg_hi:[0,1]
	v_pk_fma_f32 v[88:89], v[72:73], s[28:29], v[86:87] op_sel_hi:[1,0,1] neg_lo:[0,0,1] neg_hi:[0,0,1]
	v_pk_add_f32 v[68:69], v[70:71], v[68:69] neg_lo:[0,1] neg_hi:[0,1]
	v_pk_fma_f32 v[72:73], v[72:73], s[30:31], v[88:89] op_sel_hi:[1,0,1]
	v_pk_add_f32 v[76:77], v[66:67], v[68:69]
	v_mov_b32_e32 v71, v69
	v_mov_b32_e32 v67, v77
	v_mov_b32_e32 v69, v75
	v_pk_add_f32 v[88:89], v[86:87], v[72:73]
	v_mov_b32_e32 v70, v86
	v_mov_b32_e32 v90, v72
	v_pk_add_f32 v[66:67], v[66:67], v[68:69]
; #define LAS __attribute__((address_space(3)))
; __device__ __forceinline__ void mixer_b_unit(const Args& a, LAS unsigned char* lds, int unit) {
;     ...
;     for (int e = 0; e < 4; ++e) { const int col = OC + 16 * cb + 4 * fq + e; const float sp = -8.0f * log1pf(expf(-a.in[13][col]));
;         ba2[e >> 1][e & 1] = -1.4426950409f * a.in[10][col]; bx2[e >> 1][e & 1] = -1.4426950409f * a.in[12][col]; spl2[e >> 1][e & 1] = 1.4426950409f * sp; spy2[e >> 1][e & 1] = 2.0f * sp; }
;     const int cg = tid & 31, rg = tid >> 5;
;     LAS float* ctab = (LAS float*)(lds + MB_CTAB);
;     for (int i = tid; i < 5 * LHD; i += NWAVES * 64) { const int k = i >> 8, c = i & 255; ctab[i] = (k < 4) ? a.in[7][(size_t)k * LW + HC + c] : a.in[8][HC + c]; }
;     LAS f32x2* ag = (LAS f32x2*)(lds + MB_AG);
;     LAS unsigned* cscr = (LAS unsigned*)(lds + MB_CVT + wave * (3 * 32 * 17 * 4));
;     const int c8 = lane & 7, rgp = lane >> 3;
;     float carry = 0.f;
;     const bf16* xrp = XR + ((size_t)b * SEQ + 4 * rg) * LW + HC + 8 * cg;
;     u32x4 raw[7];
; #pragma unroll
;     for (int i = 0; i < 7; ++i) raw[i] = (4 * rg - 3 + i >= 0) ? *(const u32x4*)(xrp + (ptrdiff_t)(i - 3) * LW) : (u32x4){0u, 0u, 0u, 0u};
;     const int sidu = (unit * MB_STEPS * NWAVES + wave) * CV_SLOTS;
	v_pk_add_f32 v[68:69], v[74:75], v[76:77]
	v_pk_add_f32 v[70:71], v[70:71], v[90:91]
	v_mov_b32_e32 v90, v88
	v_mov_b32_e32 v91, v87
	v_mov_b32_e32 v92, v68
	v_mov_b32_e32 v93, v73
	v_mov_b32_e32 v96, v88
	v_mov_b32_e32 v97, v75
	v_mov_b32_e32 v98, v68
	v_mov_b32_e32 v99, v77
	v_pk_add_f32 v[94:95], v[90:91], v[92:93]
	v_pk_add_f32 v[96:97], v[96:97], v[98:99]
	v_pk_add_f32 v[98:99], v[88:89], v[68:69]
	v_pk_add_f32 v[90:91], v[94:95], v[90:91] neg_lo:[0,1] neg_hi:[0,1]
	v_mov_b32_e32 v94, v68
	v_mov_b32_e32 v95, v99
	v_mov_b32_e32 v100, v74
	v_mov_b32_e32 v101, v89
	v_pk_add_f32 v[94:95], v[94:95], v[100:101] neg_lo:[0,1] neg_hi:[0,1]
	v_mov_b32_e32 v100, v88
	v_mov_b32_e32 v101, v99
	v_mov_b32_e32 v87, v95
	v_pk_add_f32 v[86:87], v[100:101], v[86:87] neg_lo:[0,1] neg_hi:[0,1]
	v_pk_add_f32 v[92:93], v[92:93], v[90:91] neg_lo:[0,1] neg_hi:[0,1]
	v_mov_b32_e32 v100, v86
	v_mov_b32_e32 v101, v91
	v_mov_b32_e32 v91, v75
	v_pk_add_f32 v[100:101], v[72:73], v[100:101] neg_lo:[0,1] neg_hi:[0,1]
	v_pk_add_f32 v[90:91], v[96:97], v[90:91] neg_lo:[0,1] neg_hi:[0,1]
	v_mov_b32_e32 v73, v89
	v_pk_add_f32 v[70:71], v[70:71], v[90:91] neg_lo:[0,1] neg_hi:[0,1]
	v_pk_add_f32 v[72:73], v[72:73], v[86:87] neg_lo:[0,1] neg_hi:[0,1]
	v_pk_add_f32 v[66:67], v[66:67], v[94:95] neg_lo:[0,1] neg_hi:[0,1]
	v_pk_add_f32 v[68:69], v[68:69], v[74:75] neg_lo:[0,1] neg_hi:[0,1]
	v_pk_add_f32 v[74:75], v[66:67], v[72:73]
	v_mov_b32_e32 v67, v71
	v_pk_add_f32 v[68:69], v[76:77], v[68:69] neg_lo:[0,1] neg_hi:[0,1]
	v_pk_add_f32 v[76:77], v[92:93], v[70:71]
	v_pk_add_f32 v[66:67], v[100:101], v[66:67]
	v_mov_b32_e32 v73, v93
	v_pk_add_f32 v[66:67], v[66:67], v[72:73] neg_lo:[0,1] neg_hi:[0,1]
	v_mov_b32_e32 v70, v74
	v_mov_b32_e32 v71, v77
	v_pk_add_f32 v[70:71], v[70:71], v[66:67] neg_lo:[0,1] neg_hi:[0,1]
	v_pk_add_f32 v[66:67], v[68:69], v[66:67] neg_lo:[0,1] neg_hi:[0,1]
	v_pk_add_f32 v[70:71], v[72:73], v[70:71] neg_lo:[0,1] neg_hi:[0,1]
	v_pk_add_f32 v[68:69], v[76:77], v[74:75]
	v_pk_add_f32 v[66:67], v[66:67], v[70:71]
	v_pk_add_f32 v[70:71], v[98:99], v[68:69]
	v_lshrrev_b32_e32 v74, 1, v2
	v_pk_add_f32 v[72:73], v[70:71], v[98:99] neg_lo:[0,1] neg_hi:[0,1]
	v_and_b32_e32 v74, 28, v74
	v_pk_add_f32 v[68:69], v[68:69], v[72:73] neg_lo:[0,1] neg_hi:[0,1]
	v_and_b32_e32 v76, 3, v78
	v_pk_add_f32 v[66:67], v[66:67], v[68:69]
	v_add_u32_e32 v74, s4, v74
	v_pk_add_f32 v[66:67], v[70:71], v[66:67]
	v_lshl_add_u32 v77, v76, 4, s4
	v_cndmask_b32_e32 v66, v139, v66, vcc
	v_cmp_neq_f32_e32 vcc, s0, v103
	v_readlane_b32 s0, v238, 52
	s_movk_i32 s4, 0x208
	v_cndmask_b32_e32 v67, v139, v67, vcc
	v_cmp_lt_f32_e64 vcc, |v103|, s7
	v_lshl_add_u32 v158, v81, 2, s0
	s_ashr_i32 s0, s14, 3
	v_cndmask_b32_e32 v67, v67, v103, vcc
	v_cmp_lt_f32_e64 vcc, |v102|, s7
	s_andn2_b32 s0, s0, 31
	v_or_b32_e32 v69, s0, v84
	v_cndmask_b32_e32 v66, v66, v102, vcc
	s_lshl_b32 s0, s12, 6
	v_pk_mul_f32 v[66:67], v[66:67], s[34:35] op_sel_hi:[1,0]
	s_add_i32 s0, s0, 0
	v_pk_add_f32 v[134:135], v[66:67], v[66:67]
	v_pk_mul_f32 v[136:137], v[66:67], s[74:75] op_sel_hi:[1,0]
	v_lshlrev_b32_e32 v66, 2, v2
	v_or_b32_e32 v70, s15, v84
	v_lshl_add_u32 v73, v157, 3, s0
	v_cmp_gt_u32_e64 s[0:1], 8, v2
	v_mul_lo_u32 v84, v69, s4
	v_cmp_gt_u32_e64 s[4:5], 16, v2
	v_cmp_gt_u32_e64 s[6:7], 32, v2
	v_lshlrev_b32_e32 v2, 12, v78
	v_and_b32_e32 v2, 0x38000, v2
	v_or_b32_e32 v2, s2, v2
	s_lshl_b32 s24, s12, 3
	v_or_b32_e32 v2, s11, v2
	v_and_b32_e32 v68, 56, v78
	s_ashr_i32 s25, s24, 31
	v_mov_b32_e32 v71, s26
	v_lshl_or_b32 v2, s16, 6, v2
	v_lshl_add_u32 v67, v79, 4, 0
	v_and_b32_e32 v66, 28, v66
	v_mad_u32_u24 v70, v70, s46, v71
	v_or_b32_e32 v71, s13, v85
	v_lshl_add_u32 v72, v85, 3, 0
	v_mul_lo_u32 v79, v80, s46
	v_or_b32_e32 v80, 3, v83
	v_mul_lo_u32 v81, v69, s46
	v_mul_u32_u24_e32 v85, 0x208, v68
	v_lshl_add_u64 v[68:69], s[24:25], 0, v[2:3]
	v_lshl_add_u32 v71, v71, 1, 0
	v_mul_u32_u24_e32 v75, 0x44, v66
	v_lshlrev_b32_e32 v140, 3, v76
	v_mul_u32_u24_e32 v76, 0x44, v159
	v_mul_lo_u32 v80, v80, s46
	v_add_u32_e32 v83, 0, v82
	v_or_b32_e32 v68, v68, v157
	v_lshl_add_u64 v[142:143], v[68:69], 1, s[44:45]
	v_add_u32_e32 v161, v67, v79
	v_add_u32_e32 v162, v67, v80
	v_lshlrev_b32_e32 v144, 2, v66
	v_add_u32_e32 v163, v70, v82
	v_add_u32_e32 v164, v83, v81
	v_add_u32_e32 v165, v71, v81
	v_add_u32_e32 v166, v72, v84
	v_add_u32_e32 v167, v73, v85
	v_add_u32_e32 v168, v74, v75
	v_add_u32_e32 v169, v77, v76
	s_branch .LBB0_625

; __device__ __forceinline__ unsigned cvt_pk_bf16(float lo, float hi) { unsigned r; asm volatile("v_cvt_pk_bf16_f32 %0, %1, %2" : "=v"(r) : "v"(lo), "v"(hi)); return r; }
; __device__ __forceinline__ float bf_lo(unsigned w) { return __uint_as_float(w << 16); }
; __device__ __forceinline__ float bf_hi(unsigned w) { return __uint_as_float(w & 0xffff0000u); }
; #define LAS __attribute__((address_space(3)))
; __device__ __forceinline__ void mixer_b_unit(const Args& a, LAS unsigned char* lds, int unit) {
;     ...
;         { f32x4 cw[5][2];
; #pragma unroll
;           for (int k = 0; k < 5; ++k) { cw[k][0] = *(const LAS f32x4*)(ctab + k * LHD + 8 * cg); cw[k][1] = *(const LAS f32x4*)(ctab + k * LHD + 8 * cg + 4); }
; #pragma unroll
;           for (int r = 0; r < 4; ++r) { float o[8];
; #pragma unroll
;               for (int j = 0; j < 8; ++j) o[j] = cw[4][j >> 2][j & 3];
; #pragma unroll
;               for (int k = 0; k < 4; ++k) { const u32x4 w = raw[r + k];
;                   o[0] += cw[k][0][0] * bf_lo(w.x); o[1] += cw[k][0][1] * bf_hi(w.x); o[2] += cw[k][0][2] * bf_lo(w.y); o[3] += cw[k][0][3] * bf_hi(w.y);
;                   o[4] += cw[k][1][0] * bf_lo(w.z); o[5] += cw[k][1][1] * bf_hi(w.z); o[6] += cw[k][1][2] * bf_lo(w.w); o[7] += cw[k][1][3] * bf_hi(w.w); }
;               u32x4 p; p.x = cvt_pk_bf16(o[0], o[1]); p.y = cvt_pk_bf16(o[2], o[3]); p.z = cvt_pk_bf16(o[4], o[5]); p.w = cvt_pk_bf16(o[6], o[7]);
;               *(LAS u32x4*)(lds + MB_XC + (4 * rg + r) * MB_XPITCH + 16 * cg) = p; } }
.LBB0_625:
	s_waitcnt vmcnt(8)
	ds_read_b128 v[82:85], v158
	ds_read_b128 v[74:77], v158 offset:16
	ds_read_b128 v[92:95], v158 offset:1024
	ds_read_b128 v[96:99], v158 offset:1040
	ds_read_b128 v[70:73], v158 offset:2048
	ds_read_b128 v[66:69], v158 offset:2064
	ds_read_b128 v[100:103], v158 offset:3072
	ds_read_b128 v[104:107], v158 offset:3088
	ds_read_b128 v[86:89], v158 offset:4096
	ds_read_b128 v[78:81], v158 offset:4112
	v_lshlrev_b32_e32 v108, 16, v62
	v_lshlrev_b32_e32 v109, 16, v54
	s_waitcnt lgkmcnt(7)
	v_mov_b32_e32 v90, v92
	v_mov_b32_e32 v91, v82
	v_pk_mul_f32 v[110:111], v[90:91], v[108:109]
	v_mov_b32_e32 v82, v93
	s_waitcnt lgkmcnt(1)
	v_add_f32_e32 v2, v111, v86
	v_add_f32_e32 v2, v110, v2
	v_and_b32_e32 v111, 0xffff0000, v54
	v_and_b32_e32 v110, 0xffff0000, v62
	v_pk_mul_f32 v[92:93], v[82:83], v[110:111]
	v_lshlrev_b32_e32 v112, 16, v63
	v_add_f32_e32 v54, v93, v87
	v_add_f32_e32 v109, v92, v54
	v_lshlrev_b32_e32 v113, 16, v55
	v_mov_b32_e32 v92, v94
	v_mov_b32_e32 v93, v84
	v_pk_mul_f32 v[114:115], v[92:93], v[112:113]
	v_mov_b32_e32 v84, v95
	v_add_f32_e32 v54, v115, v88
	v_add_f32_e32 v113, v114, v54
	v_and_b32_e32 v115, 0xffff0000, v55
	v_and_b32_e32 v114, 0xffff0000, v63
	v_pk_mul_f32 v[54:55], v[84:85], v[114:115]
	v_lshlrev_b32_e32 v94, 16, v64
	v_add_f32_e32 v55, v55, v89
	v_add_f32_e32 v145, v54, v55
	v_lshlrev_b32_e32 v95, 16, v56
	v_mov_b32_e32 v54, v96
	v_mov_b32_e32 v55, v74
	v_pk_mul_f32 v[62:63], v[54:55], v[94:95]
	v_and_b32_e32 v117, 0xffff0000, v56
	s_waitcnt lgkmcnt(0)
	v_add_f32_e32 v63, v63, v78
	v_and_b32_e32 v116, 0xffff0000, v64
	v_mov_b32_e32 v74, v97
	v_add_f32_e32 v95, v62, v63
	v_pk_mul_f32 v[62:63], v[74:75], v[116:117]
	v_lshlrev_b32_e32 v96, 16, v65
	v_add_f32_e32 v56, v63, v79
	v_add_f32_e32 v150, v62, v56
	v_lshlrev_b32_e32 v97, 16, v57
	v_mov_b32_e32 v62, v98
	v_mov_b32_e32 v63, v76
	v_pk_mul_f32 v[118:119], v[62:63], v[96:97]
	v_mov_b32_e32 v76, v99
	v_add_f32_e32 v56, v119, v80
	v_add_f32_e32 v97, v118, v56
	v_and_b32_e32 v119, 0xffff0000, v57
	v_and_b32_e32 v118, 0xffff0000, v65
	v_pk_mul_f32 v[56:57], v[76:77], v[118:119]
	v_lshlrev_b32_e32 v99, 16, v50
	v_add_f32_e32 v57, v57, v81
	v_add_f32_e32 v152, v56, v57
	v_lshlrev_b32_e32 v98, 16, v58
	v_mov_b32_e32 v56, v100
	v_mov_b32_e32 v57, v70
	v_pk_mul_f32 v[64:65], v[56:57], v[98:99]
	v_and_b32_e32 v121, 0xffff0000, v50
	v_add_f32_e32 v2, v65, v2
	v_and_b32_e32 v120, 0xffff0000, v58
	v_mov_b32_e32 v70, v101
	v_add_f32_e32 v2, v64, v2
	v_pk_mul_f32 v[64:65], v[70:71], v[120:121]
	v_lshlrev_b32_e32 v101, 16, v51
	v_add_f32_e32 v50, v65, v109
	v_add_f32_e32 v109, v64, v50
	v_lshlrev_b32_e32 v100, 16, v59
	v_mov_b32_e32 v64, v102
	v_mov_b32_e32 v65, v72
	v_pk_mul_f32 v[146:147], v[64:65], v[100:101]
	v_mov_b32_e32 v72, v103
	v_add_f32_e32 v50, v147, v113
	v_add_f32_e32 v113, v146, v50
	v_and_b32_e32 v147, 0xffff0000, v51
	v_and_b32_e32 v146, 0xffff0000, v59
	v_pk_mul_f32 v[50:51], v[72:73], v[146:147]
	v_lshlrev_b32_e32 v103, 16, v52
	v_add_f32_e32 v51, v51, v145
	v_add_f32_e32 v145, v50, v51
	v_lshlrev_b32_e32 v102, 16, v60
	v_mov_b32_e32 v50, v104
	v_mov_b32_e32 v51, v66
	v_pk_mul_f32 v[58:59], v[50:51], v[102:103]
	v_and_b32_e32 v149, 0xffff0000, v52
	v_add_f32_e32 v59, v59, v95
	v_and_b32_e32 v148, 0xffff0000, v60
	v_mov_b32_e32 v66, v105
	v_add_f32_e32 v95, v58, v59
	v_pk_mul_f32 v[58:59], v[66:67], v[148:149]
	v_lshlrev_b32_e32 v105, 16, v53
	v_add_f32_e32 v52, v59, v150
	v_lshlrev_b32_e32 v104, 16, v61
	v_mov_b32_e32 v150, v106
	v_mov_b32_e32 v151, v68
	v_add_f32_e32 v60, v58, v52
	v_pk_mul_f32 v[58:59], v[150:151], v[104:105]
	v_and_b32_e32 v53, 0xffff0000, v53
	v_add_f32_e32 v52, v59, v97
	v_add_f32_e32 v97, v58, v52
	v_and_b32_e32 v52, 0xffff0000, v61
	v_mov_b32_e32 v68, v107
	v_pk_mul_f32 v[58:59], v[68:69], v[52:53]
	s_mov_b32 s2, 0x2e800000
	v_add_f32_e32 v59, v59, v152
	v_add_f32_e32 v61, v58, v59
	v_cvt_pk_bf16_f32 v58, v2, v109
	v_cvt_pk_bf16_f32 v59, v113, v145
	v_cvt_pk_bf16_f32 v60, v95, v60
	v_cvt_pk_bf16_f32 v61, v97, v61
	ds_write_b128 v161, v[58:61]
	v_pk_mov_b32 v[58:59], v[98:99], v[108:109] op_sel:[1,0]
	s_cmp_lg_u32 s86, 0xf80000
	v_pk_mul_f32 v[58:59], v[90:91], v[58:59]
	s_cselect_b32 s18, s51, 0x7bd
	v_add_f32_e32 v2, v59, v86
	v_add_f32_e32 v2, v58, v2
	v_pk_mov_b32 v[58:59], v[120:121], v[110:111] op_sel:[1,0]
	s_nop 0
	v_pk_mul_f32 v[58:59], v[82:83], v[58:59]
	s_nop 0
	v_add_f32_e32 v59, v59, v87
	v_add_f32_e32 v106, v58, v59
	v_pk_mov_b32 v[58:59], v[100:101], v[112:113] op_sel:[1,0]
	s_nop 0
	v_pk_mul_f32 v[58:59], v[92:93], v[58:59]
	s_nop 0
	v_add_f32_e32 v59, v59, v88
	v_add_f32_e32 v108, v58, v59
	v_pk_mov_b32 v[58:59], v[146:147], v[114:115] op_sel:[1,0]
	s_nop 0
	v_pk_mul_f32 v[58:59], v[84:85], v[58:59]
	s_nop 0
	v_add_f32_e32 v59, v59, v89
	v_add_f32_e32 v110, v58, v59
	v_pk_mov_b32 v[58:59], v[102:103], v[94:95] op_sel:[1,0]
	s_nop 0
	v_pk_mul_f32 v[58:59], v[54:55], v[58:59]
	s_nop 0
	v_add_f32_e32 v59, v59, v78
	v_add_f32_e32 v112, v58, v59
	v_pk_mov_b32 v[58:59], v[148:149], v[116:117] op_sel:[1,0]
	s_nop 0
	v_pk_mul_f32 v[58:59], v[74:75], v[58:59]
	s_nop 0
	v_add_f32_e32 v59, v59, v79
	v_add_f32_e32 v116, v58, v59
	v_pk_mov_b32 v[58:59], v[104:105], v[96:97] op_sel:[1,0]
	s_nop 0
	v_pk_mul_f32 v[58:59], v[62:63], v[58:59]
	s_nop 0
	v_add_f32_e32 v59, v59, v80
	v_add_f32_e32 v145, v58, v59
	v_pk_mov_b32 v[58:59], v[52:53], v[118:119] op_sel:[1,0]
	s_nop 0
	v_pk_mul_f32 v[58:59], v[76:77], v[58:59]
	s_nop 0
	v_add_f32_e32 v59, v59, v81
	v_add_f32_e32 v118, v58, v59
	v_pk_mul_f32 v[58:59], v[90:91], v[98:99]
	s_nop 0
	v_add_f32_e32 v59, v59, v86
	v_add_f32_e32 v96, v58, v59
; __device__ __forceinline__ unsigned cvt_pk_bf16(float lo, float hi) { unsigned r; asm volatile("v_cvt_pk_bf16_f32 %0, %1, %2" : "=v"(r) : "v"(lo), "v"(hi)); return r; }
; __device__ __forceinline__ float bf_lo(unsigned w) { return __uint_as_float(w << 16); }
; __device__ __forceinline__ float bf_hi(unsigned w) { return __uint_as_float(w & 0xffff0000u); }
; #define LAS __attribute__((address_space(3)))
; __device__ __forceinline__ void mixer_b_unit(const Args& a, LAS unsigned char* lds, int unit) {
;     ...
;         { f32x4 cw[5][2];
; #pragma unroll
;           for (int k = 0; k < 5; ++k) { cw[k][0] = *(const LAS f32x4*)(ctab + k * LHD + 8 * cg); cw[k][1] = *(const LAS f32x4*)(ctab + k * LHD + 8 * cg + 4); }
; #pragma unroll
;           for (int r = 0; r < 4; ++r) { float o[8];
; #pragma unroll
;               for (int j = 0; j < 8; ++j) o[j] = cw[4][j >> 2][j & 3];
; #pragma unroll
;               for (int k = 0; k < 4; ++k) { const u32x4 w = raw[r + k];
;                   o[0] += cw[k][0][0] * bf_lo(w.x); o[1] += cw[k][0][1] * bf_hi(w.x); o[2] += cw[k][0][2] * bf_lo(w.y); o[3] += cw[k][0][3] * bf_hi(w.y);
;                   o[4] += cw[k][1][0] * bf_lo(w.z); o[5] += cw[k][1][1] * bf_hi(w.z); o[6] += cw[k][1][2] * bf_lo(w.w); o[7] += cw[k][1][3] * bf_hi(w.w); }
;               u32x4 p; p.x = cvt_pk_bf16(o[0], o[1]); p.y = cvt_pk_bf16(o[2], o[3]); p.z = cvt_pk_bf16(o[4], o[5]); p.w = cvt_pk_bf16(o[6], o[7]);
;               *(LAS u32x4*)(lds + MB_XC + (4 * rg + r) * MB_XPITCH + 16 * cg) = p; } }
	v_pk_mul_f32 v[58:59], v[82:83], v[120:121]
	s_nop 0
	v_add_f32_e32 v59, v59, v87
	v_add_f32_e32 v107, v58, v59
	v_pk_mul_f32 v[58:59], v[92:93], v[100:101]
	s_nop 0
	v_add_f32_e32 v59, v59, v88
	v_add_f32_e32 v109, v58, v59
	v_pk_mul_f32 v[58:59], v[84:85], v[146:147]
	s_nop 0
	v_add_f32_e32 v59, v59, v89
	v_add_f32_e32 v111, v58, v59
	v_pk_mul_f32 v[58:59], v[54:55], v[102:103]
	s_nop 0
	v_add_f32_e32 v59, v59, v78
	v_add_f32_e32 v113, v58, v59
	v_pk_mul_f32 v[58:59], v[74:75], v[148:149]
	s_nop 0
	v_add_f32_e32 v59, v59, v79
	v_add_f32_e32 v117, v58, v59
	v_pk_mul_f32 v[58:59], v[62:63], v[104:105]
	s_nop 0
	v_add_f32_e32 v59, v59, v80
	v_add_f32_e32 v119, v58, v59
	v_pk_mul_f32 v[58:59], v[76:77], v[52:53]
	s_nop 0
	v_add_f32_e32 v59, v59, v81
	v_add_f32_e32 v152, v58, v59
	v_lshlrev_b32_e32 v59, 16, v42
	v_lshlrev_b32_e32 v58, 16, v46
	v_pk_mov_b32 v[60:61], v[58:59], v[98:99] op_sel:[1,0]
	s_nop 0
	v_pk_mul_f32 v[94:95], v[56:57], v[60:61]
	s_nop 0
	v_add_f32_e32 v2, v95, v2
	v_add_f32_e32 v2, v94, v2
	v_pk_mul_f32 v[94:95], v[56:57], v[58:59]
	s_nop 0
	v_add_f32_e32 v59, v95, v96
	v_add_f32_e32 v59, v94, v59
	v_and_b32_e32 v95, 0xffff0000, v42
	v_and_b32_e32 v94, 0xffff0000, v46
	v_pk_mov_b32 v[96:97], v[94:95], v[120:121] op_sel:[1,0]
	s_nop 0
	v_pk_mul_f32 v[98:99], v[70:71], v[96:97]
	s_nop 0
	v_add_f32_e32 v42, v99, v106
	v_add_f32_e32 v42, v98, v42
	v_pk_mul_f32 v[98:99], v[70:71], v[94:95]
	v_cvt_pk_bf16_f32 v42, v2, v42
	s_nop 0
	v_add_f32_e32 v46, v99, v107
	v_add_f32_e32 v2, v98, v46
	v_lshlrev_b32_e32 v99, 16, v43
	v_lshlrev_b32_e32 v98, 16, v47
	v_pk_mov_b32 v[100:101], v[98:99], v[100:101] op_sel:[1,0]
	s_nop 0
	v_pk_mul_f32 v[106:107], v[64:65], v[100:101]
	s_nop 0
	v_add_f32_e32 v46, v107, v108
	v_add_f32_e32 v95, v106, v46
	v_pk_mul_f32 v[106:107], v[64:65], v[98:99]
	s_nop 0
	v_add_f32_e32 v46, v107, v109
	v_add_f32_e32 v99, v106, v46
	v_and_b32_e32 v107, 0xffff0000, v43
	v_and_b32_e32 v106, 0xffff0000, v47
	v_pk_mov_b32 v[46:47], v[106:107], v[146:147] op_sel:[1,0]
	v_lshl_add_u64 v[146:147], v[142:143], 0, s[86:87]
	v_pk_mul_f32 v[108:109], v[72:73], v[46:47]
	s_nop 0
	v_add_f32_e32 v43, v109, v110
	v_add_f32_e32 v43, v108, v43
	v_pk_mul_f32 v[108:109], v[72:73], v[106:107]
	v_cvt_pk_bf16_f32 v43, v95, v43
	s_nop 0
	v_add_f32_e32 v107, v109, v111
	v_add_f32_e32 v95, v108, v107
	v_lshlrev_b32_e32 v109, 16, v44
	v_lshlrev_b32_e32 v108, 16, v48
	v_pk_mov_b32 v[102:103], v[108:109], v[102:103] op_sel:[1,0]
	s_nop 0
	v_pk_mul_f32 v[110:111], v[50:51], v[102:103]
	s_nop 0
	v_add_f32_e32 v107, v111, v112
	v_add_f32_e32 v107, v110, v107
	v_pk_mul_f32 v[110:111], v[50:51], v[108:109]
	s_nop 0
	v_add_f32_e32 v109, v111, v113
	v_add_f32_e32 v109, v110, v109
	v_and_b32_e32 v111, 0xffff0000, v44
	v_and_b32_e32 v110, 0xffff0000, v48
	v_pk_mov_b32 v[112:113], v[110:111], v[148:149] op_sel:[1,0]
	s_nop 0
	v_pk_mul_f32 v[114:115], v[66:67], v[112:113]
	s_nop 0
	v_add_f32_e32 v44, v115, v116
	v_add_f32_e32 v44, v114, v44
	v_pk_mul_f32 v[114:115], v[66:67], v[110:111]
	v_cvt_pk_bf16_f32 v44, v107, v44
	s_nop 0
	v_add_f32_e32 v48, v115, v117
	v_add_f32_e32 v107, v114, v48
	v_lshlrev_b32_e32 v115, 16, v45
	v_lshlrev_b32_e32 v114, 16, v49
	v_pk_mov_b32 v[104:105], v[114:115], v[104:105] op_sel:[1,0]
	s_nop 0
	v_pk_mul_f32 v[116:117], v[150:151], v[104:105]
	s_nop 0
	v_add_f32_e32 v48, v117, v145
	v_add_f32_e32 v111, v116, v48
	v_pk_mul_f32 v[116:117], v[150:151], v[114:115]
	s_nop 0
	v_add_f32_e32 v48, v117, v119
	v_add_f32_e32 v115, v116, v48
	v_and_b32_e32 v117, 0xffff0000, v45
	v_and_b32_e32 v116, 0xffff0000, v49
	v_pk_mov_b32 v[48:49], v[116:117], v[52:53] op_sel:[1,0]
	s_nop 0
	v_pk_mul_f32 v[52:53], v[68:69], v[48:49]
	s_nop 0
	v_add_f32_e32 v45, v53, v118
	v_add_f32_e32 v45, v52, v45
	v_pk_mul_f32 v[52:53], v[68:69], v[116:117]
	v_cvt_pk_bf16_f32 v45, v111, v45
	ds_write_b128 v161, v[42:45] offset:528
	v_add_f32_e32 v53, v53, v152
	v_add_f32_e32 v45, v52, v53
	v_cvt_pk_bf16_f32 v42, v59, v2
	v_cvt_pk_bf16_f32 v43, v99, v95
	v_cvt_pk_bf16_f32 v44, v109, v107
	v_cvt_pk_bf16_f32 v45, v115, v45
	ds_write_b128 v161, v[42:45] offset:1056
	v_pk_mul_f32 v[42:43], v[90:91], v[60:61]
	s_nop 0
	v_add_f32_e32 v2, v43, v86
	v_add_f32_e32 v2, v42, v2
	v_pk_mul_f32 v[42:43], v[82:83], v[96:97]
	s_nop 0
	v_add_f32_e32 v43, v43, v87
	v_add_f32_e32 v44, v42, v43
	v_pk_mul_f32 v[42:43], v[92:93], v[100:101]
	s_nop 0
	v_add_f32_e32 v43, v43, v88
	v_add_f32_e32 v45, v42, v43
	v_pk_mul_f32 v[42:43], v[84:85], v[46:47]
	s_nop 0
	v_add_f32_e32 v43, v43, v89
	v_add_f32_e32 v46, v42, v43
	v_pk_mul_f32 v[42:43], v[54:55], v[102:103]
	s_nop 0
	v_add_f32_e32 v43, v43, v78
	v_add_f32_e32 v47, v42, v43
	v_pk_mul_f32 v[42:43], v[74:75], v[112:113]
	s_nop 0
	v_add_f32_e32 v43, v43, v79
	v_add_f32_e32 v52, v42, v43
	v_pk_mul_f32 v[42:43], v[62:63], v[104:105]
	s_nop 0
	v_add_f32_e32 v43, v43, v80
	v_add_f32_e32 v53, v42, v43
	v_pk_mul_f32 v[42:43], v[76:77], v[48:49]
	s_nop 0
	v_add_f32_e32 v43, v43, v81
	v_add_f32_e32 v48, v42, v43
	v_lshlrev_b32_e32 v42, 16, v38
	v_mov_b32_e32 v43, v58
	v_pk_mul_f32 v[42:43], v[56:57], v[42:43]
	s_nop 0
	v_add_f32_e32 v2, v43, v2
	v_add_f32_e32 v2, v42, v2
	v_and_b32_e32 v42, 0xffff0000, v38
	v_mov_b32_e32 v43, v94
	v_pk_mul_f32 v[42:43], v[70:71], v[42:43]
	s_nop 0
	v_add_f32_e32 v38, v43, v44
	v_add_f32_e32 v44, v42, v38
	v_lshlrev_b32_e32 v42, 16, v39
	v_mov_b32_e32 v43, v98
	v_pk_mul_f32 v[42:43], v[64:65], v[42:43]
	s_nop 0
	v_add_f32_e32 v38, v43, v45
	v_add_f32_e32 v42, v42, v38
	v_and_b32_e32 v38, 0xffff0000, v39
	v_mov_b32_e32 v39, v106
	v_pk_mul_f32 v[38:39], v[72:73], v[38:39]
	s_nop 0
	v_add_f32_e32 v39, v39, v46
; #define LAS __attribute__((address_space(3)))
; __device__ __forceinline__ CvtTile cvt_decode(const Args& a, int t) {
;     CvtTile c; c.src = a.in[18]; c.dst = nullptr; c.gain = a.in[17]; c.ldw = 0; c.ldt = 0; c.valid = 0; c.has_gain = 0;
;     if (t < CV_UP) { const int kb = t % (DM / 32), nb = t / (DM / 32); const int n0 = 32 * nb; const int ch = (n0 < FFW) ? n0 : n0 - FFW; const int dn0 = (ch >> 7) * 256 + (ch & 127) + ((n0 < FFW) ? 0 : 128);
;         c.src = a.in[18] + (size_t)(32 * kb) * UPN + n0; c.dst = (bf16*)(a.ws + WS_WUP) + (size_t)dn0 * DM + 32 * kb; c.gain = a.in[17] + 32 * kb; c.ldw = UPN; c.ldt = DM; c.valid = 1; c.has_gain = 1; return c; }
;     const float* W; bf16* WT; int KB, N, K;
;     if ((t -= CV_UP) < CV_PB) { W = a.in[15]; WT = (bf16*)(a.ws + WS_PB); KB = LW / 32; N = DM; K = LW; }
;     else if ((t -= CV_PB) < CV_WO) { W = a.in[16]; WT = (bf16*)(a.ws + WS_WOUT); KB = DM / 32; N = DM; K = DM; }
;     else return c;
;     const int kb = t % KB, nb = t / KB;
; __device__ __forceinline__ void mixer_b_unit(const Args& a, LAS unsigned char* lds, int unit) {
;     ...
;               for (int k = 0; k < 4; ++k) { const u32x4 w = raw[r + k];
;                   o[0] += cw[k][0][0] * bf_lo(w.x); o[1] += cw[k][0][1] * bf_hi(w.x); o[2] += cw[k][0][2] * bf_lo(w.y); o[3] += cw[k][0][3] * bf_hi(w.y);
;                   o[4] += cw[k][1][0] * bf_lo(w.z); o[5] += cw[k][1][1] * bf_hi(w.z); o[6] += cw[k][1][2] * bf_lo(w.w); o[7] += cw[k][1][3] * bf_hi(w.w); }
;               u32x4 p; p.x = cvt_pk_bf16(o[0], o[1]); p.y = cvt_pk_bf16(o[2], o[3]); p.z = cvt_pk_bf16(o[4], o[5]); p.w = cvt_pk_bf16(o[6], o[7]);
;               *(LAS u32x4*)(lds + MB_XC + (4 * rg + r) * MB_XPITCH + 16 * cg) = p; } }
;         const size_t gb = (rowbase + 8 * rgp) * LW + OC + 8 * wave + c8;
;         unsigned short yr[8];
; #pragma unroll
;         for (int i = 0; i < 8; ++i) yr[i] = GYR[gb + (size_t)i * LW];
;         { const int tn = more ? t0 + MBT : t0;
; #pragma unroll
;           for (int i = 0; i < 7; ++i) raw[i] = *(const u32x4*)(xrp + (ptrdiff_t)(tn + i - 3) * LW); }
;         f32x4 cvA[4], cvB[4], cvC[4]; f32x2c glA[2], glB[2], glC[2];
;         const int sid = sidu + step * NWAVES * CV_SLOTS;
;         const CvtTile ctA = cvt_decode(a, sid), ctB = cvt_decode(a, sid + 1), ctC = cvt_decode3(a, (unit * MB_STEPS + step) * NWAVES + wave);
	v_add_f32_e32 v43, v38, v39
	v_lshlrev_b32_e32 v38, 16, v40
	v_mov_b32_e32 v39, v108
	v_pk_mul_f32 v[38:39], v[50:51], v[38:39]
	s_nop 0
	v_add_f32_e32 v39, v39, v47
	v_add_f32_e32 v45, v38, v39
	v_and_b32_e32 v38, 0xffff0000, v40
	v_mov_b32_e32 v39, v110
	v_pk_mul_f32 v[38:39], v[66:67], v[38:39]
	s_nop 0
	v_add_f32_e32 v39, v39, v52
	v_add_f32_e32 v40, v38, v39
	v_lshlrev_b32_e32 v38, 16, v41
	v_mov_b32_e32 v39, v114
	v_pk_mul_f32 v[38:39], v[150:151], v[38:39]
	s_nop 0
	v_add_f32_e32 v39, v39, v53
	v_add_f32_e32 v46, v38, v39
	v_and_b32_e32 v38, 0xffff0000, v41
	v_mov_b32_e32 v39, v116
	v_pk_mul_f32 v[38:39], v[68:69], v[38:39]
	s_nop 0
	v_add_f32_e32 v39, v39, v48
	v_add_f32_e32 v41, v38, v39
	v_cvt_pk_bf16_f32 v38, v2, v44
	v_cvt_pk_bf16_f32 v39, v42, v43
	v_cvt_pk_bf16_f32 v40, v45, v40
	v_cvt_pk_bf16_f32 v41, v46, v41
	ds_write_b128 v162, v[38:41]
	v_add_co_u32_e32 v38, vcc, s2, v146
	s_mov_b32 s2, 0x2e802000
	s_nop 0
	v_addc_co_u32_e32 v39, vcc, 0, v147, vcc
	global_load_ushort v176, v[38:39], off
	v_add_co_u32_e32 v38, vcc, s2, v146
	s_mov_b32 s2, 0x2e804000
	s_nop 0
	v_addc_co_u32_e32 v39, vcc, 0, v147, vcc
	global_load_ushort v175, v[38:39], off
	v_add_co_u32_e32 v38, vcc, s2, v146
	s_mov_b32 s2, 0x2e806000
	s_nop 0
	v_addc_co_u32_e32 v39, vcc, 0, v147, vcc
	global_load_ushort v174, v[38:39], off
	v_add_co_u32_e32 v38, vcc, s2, v146
	s_mov_b32 s2, 0x2e808000
	s_nop 0
	v_addc_co_u32_e32 v39, vcc, 0, v147, vcc
	global_load_ushort v173, v[38:39], off
	v_add_co_u32_e32 v38, vcc, s2, v146
	s_mov_b32 s2, 0x2e80a000
	s_nop 0
	v_addc_co_u32_e32 v39, vcc, 0, v147, vcc
	global_load_ushort v172, v[38:39], off
	v_add_co_u32_e32 v38, vcc, s2, v146
	s_mov_b32 s2, 0x2e80c000
	s_nop 0
	v_addc_co_u32_e32 v39, vcc, 0, v147, vcc
	global_load_ushort v171, v[38:39], off
	v_add_co_u32_e32 v38, vcc, s2, v146
	s_mov_b32 s2, 0x2e80e000
	s_nop 0
	v_addc_co_u32_e32 v39, vcc, 0, v147, vcc
	global_load_ushort v170, v[38:39], off
	v_add_co_u32_e32 v38, vcc, s2, v146
	s_lshl_b64 s[2:3], s[18:19], 13
	s_nop 0
	v_addc_co_u32_e32 v39, vcc, 0, v147, vcc
	global_load_ushort v177, v[38:39], off
	v_lshl_add_u64 v[38:39], v[122:123], 0, s[2:3]
	s_add_i32 s2, s18, 1
	s_mov_b32 s3, s19
	s_lshl_b64 s[2:3], s[2:3], 13
	global_load_dwordx4 v[54:57], v[38:39], off
	v_lshl_add_u64 v[38:39], v[122:123], 0, s[2:3]
	s_or_b32 s2, s18, 2
	s_mov_b32 s3, s19
	s_lshl_b64 s[2:3], s[2:3], 13
	global_load_dwordx4 v[62:65], v[38:39], off
	v_lshl_add_u64 v[38:39], v[122:123], 0, s[2:3]
	s_add_i32 s2, s18, 3
	s_ashr_i32 s3, s2, 31
	s_lshl_b64 s[2:3], s[2:3], 13
	global_load_dwordx4 v[50:53], v[38:39], off
	v_lshl_add_u64 v[38:39], v[122:123], 0, s[2:3]
	s_add_i32 s2, s18, 4
	s_ashr_i32 s3, s2, 31
	s_lshl_b64 s[2:3], s[2:3], 13
	global_load_dwordx4 v[58:61], v[38:39], off
	v_lshl_add_u64 v[38:39], v[122:123], 0, s[2:3]
	s_add_i32 s2, s18, 5
	s_ashr_i32 s3, s2, 31
	s_lshl_b64 s[2:3], s[2:3], 13
	global_load_dwordx4 v[42:45], v[38:39], off
	v_lshl_add_u64 v[38:39], v[122:123], 0, s[2:3]
	s_add_i32 s2, s18, 6
	s_ashr_i32 s3, s2, 31
	s_lshl_b64 s[2:3], s[2:3], 13
	global_load_dwordx4 v[46:49], v[38:39], off
	v_lshl_add_u64 v[38:39], v[122:123], 0, s[2:3]
	global_load_dwordx4 v[38:41], v[38:39], off
	s_cmp_gt_i32 s50, 0x17fff
	s_cselect_b64 s[8:9], -1, 0
	s_mov_b64 s[2:3], -1
	s_and_b64 vcc, exec, s[8:9]
	s_cbranch_vccnz .LBB0_627
	s_ashr_i32 s2, s50, 31
	s_lshr_b32 s2, s2, 25
	s_add_i32 s2, s50, s2
	s_ashr_i32 s3, s2, 7
	s_and_b32 s2, s2, 0xffffff80
	s_sub_i32 s11, s50, s2
	s_lshl_b32 s2, s3, 5
	s_add_i32 s3, s2, 0xffffd000
	s_cmp_lt_i32 s50, 0xc000
	s_cselect_b32 s3, s2, s3
	s_cselect_b32 s10, 0, 0x80
	s_lshl_b32 s12, s3, 1
	s_and_b32 s3, s3, 0x60
	s_and_b32 s12, s12, 0xffffff00
	s_or_b32 s3, s3, s10
	s_or_b32 s10, s3, s12
	s_lshl_b32 s12, s11, 5
	v_readlane_b32 s52, v238, 28
	s_ashr_i32 s13, s12, 31
	s_mul_i32 s11, s11, 0x300000
	v_readlane_b32 s56, v238, 32
	s_mul_hi_i32 s3, s12, 0x18000
	v_readlane_b32 s57, v238, 33
	s_add_u32 s11, s56, s11
	s_addc_u32 s14, s57, s3
	s_ashr_i32 s3, s2, 31
	s_lshl_b64 s[2:3], s[2:3], 2
	s_add_u32 s30, s11, s2
	s_addc_u32 s31, s14, s3
	s_ashr_i32 s11, s10, 31
	s_lshl_b64 s[2:3], s[10:11], 13
	s_add_u32 s10, s21, s2
	s_addc_u32 s11, s75, s3
	s_lshl_b64 s[2:3], s[12:13], 1
	s_add_u32 s88, s10, s2
	v_readlane_b32 s54, v238, 30
	s_addc_u32 s89, s11, s3
	s_lshl_b64 s[2:3], s[12:13], 2
	v_readlane_b32 s55, v238, 31
	s_add_u32 s12, s54, s2
	s_addc_u32 s13, s55, s3
	s_mov_b64 s[2:3], 0
	v_readlane_b32 s53, v238, 29
	v_readlane_b32 s58, v238, 34
	v_readlane_b32 s59, v238, 35
	v_readlane_b32 s60, v238, 36
	v_readlane_b32 s61, v238, 37
	v_readlane_b32 s62, v238, 38
	v_readlane_b32 s63, v238, 39
	v_readlane_b32 s64, v238, 40
	v_readlane_b32 s65, v238, 41
	v_readlane_b32 s66, v238, 42
	v_readlane_b32 s67, v238, 43
.LBB0_627:
	s_andn2_b64 vcc, exec, s[2:3]
	s_cbranch_vccnz .LBB0_631
	s_cmp_lt_u32 s50, 0x1c000
	s_cselect_b64 s[10:11], -1, 0
	s_and_b64 vcc, exec, s[10:11]
	s_cbranch_vccnz .LBB0_632
	v_readlane_b32 s52, v238, 28
	s_cmp_lt_u32 s50, 0x20000
	v_readlane_b32 s53, v238, 29
	v_readlane_b32 s54, v238, 30
	v_readlane_b32 s55, v238, 31
	v_readlane_b32 s56, v238, 32
	v_readlane_b32 s57, v238, 33
	s_mov_b32 s16, 0xfffe4000
	s_mov_b64 s[2:3], 0x20200000
	s_cselect_b64 s[10:11], -1, 0
	s_mov_b64 s[12:13], s[54:55]
	s_mov_b64 s[30:31], s[56:57]
	s_mov_b64 s[14:15], s[52:53]
	v_readlane_b32 s58, v238, 34
	v_readlane_b32 s59, v238, 35
	v_readlane_b32 s60, v238, 36
	v_readlane_b32 s61, v238, 37
	v_readlane_b32 s62, v238, 38
	v_readlane_b32 s63, v238, 39
	v_readlane_b32 s64, v238, 40
	v_readlane_b32 s65, v238, 41
	v_readlane_b32 s66, v238, 42
	v_readlane_b32 s67, v238, 43
	s_andn2_b64 vcc, exec, s[10:11]
	s_cbranch_vccz .LBB0_633

; __device__ __forceinline__ CvtTile cvt_decode(const Args& a, int t) {
;     ...
;     const float* W; bf16* WT; int KB, N, K;
;     if ((t -= CV_UP) < CV_PB) { W = a.in[15]; WT = (bf16*)(a.ws + WS_PB); KB = LW / 32; N = DM; K = LW; }
;     else if ((t -= CV_PB) < CV_WO) { W = a.in[16]; WT = (bf16*)(a.ws + WS_WOUT); KB = DM / 32; N = DM; K = DM; }
;     else return c;
;     const int kb = t % KB, nb = t / KB;
;     c.src = W + (size_t)(32 * kb) * N + 32 * nb; c.dst = WT + (size_t)(32 * nb) * K + 32 * kb; c.ldw = N; c.ldt = K; c.valid = 1; return c;
.LBB0_633:
	s_add_i32 s10, s50, s16
	s_add_u32 s11, s44, s2
	s_addc_u32 s12, s45, s3
	s_lshl_b32 s2, s10, 5
	s_and_b32 s13, s2, 0xfc0
	s_lshl_b32 s2, s13, 14
	s_add_u32 s2, s14, s2
	s_addc_u32 s3, s15, 0
	s_lshr_b32 s10, s10, 2
	s_and_b32 s18, s10, 0x3fffffe0
	s_lshl_b32 s10, s18, 2
	s_add_u32 s30, s2, s10
	s_addc_u32 s31, s3, 0
	s_lshl_b64 s[2:3], s[18:19], 13
	s_add_u32 s2, s11, s2
	s_addc_u32 s3, s12, s3
	s_lshl_b32 s10, s13, 1
	v_readlane_b32 s52, v238, 28
	s_add_u32 s88, s2, s10
	v_readlane_b32 s54, v238, 30
	v_readlane_b32 s55, v238, 31
	s_addc_u32 s89, s3, 0
	s_mov_b64 s[90:91], 0x1000
	s_mov_b64 s[16:17], 0
	s_mov_b64 s[12:13], s[54:55]
	v_readlane_b32 s53, v238, 29
	v_readlane_b32 s56, v238, 32
	v_readlane_b32 s57, v238, 33
	v_readlane_b32 s58, v238, 34
	v_readlane_b32 s59, v238, 35
	v_readlane_b32 s60, v238, 36
	v_readlane_b32 s61, v238, 37
	v_readlane_b32 s62, v238, 38
	v_readlane_b32 s63, v238, 39
	v_readlane_b32 s64, v238, 40
	v_readlane_b32 s65, v238, 41
	v_readlane_b32 s66, v238, 42
	v_readlane_b32 s67, v238, 43

; __device__ __forceinline__ CvtTile cvt_decode(const Args& a, int t) {
;     CvtTile c; c.src = a.in[18]; c.dst = nullptr; c.gain = a.in[17]; c.ldw = 0; c.ldt = 0; c.valid = 0; c.has_gain = 0;
;     if (t < CV_UP) { const int kb = t % (DM / 32), nb = t / (DM / 32); const int n0 = 32 * nb; const int ch = (n0 < FFW) ? n0 : n0 - FFW; const int dn0 = (ch >> 7) * 256 + (ch & 127) + ((n0 < FFW) ? 0 : 128);
;         c.src = a.in[18] + (size_t)(32 * kb) * UPN + n0; c.dst = (bf16*)(a.ws + WS_WUP) + (size_t)dn0 * DM + 32 * kb; c.gain = a.in[17] + 32 * kb; c.ldw = UPN; c.ldt = DM; c.valid = 1; c.has_gain = 1; return c; }
;     const float* W; bf16* WT; int KB, N, K;
;     if ((t -= CV_UP) < CV_PB) { W = a.in[15]; WT = (bf16*)(a.ws + WS_PB); KB = LW / 32; N = DM; K = LW; }
;     else if ((t -= CV_PB) < CV_WO) { W = a.in[16]; WT = (bf16*)(a.ws + WS_WOUT); KB = DM / 32; N = DM; K = DM; }
;     else return c;
;     const int kb = t % KB, nb = t / KB;
;     c.src = W + (size_t)(32 * kb) * N + 32 * nb; c.dst = WT + (size_t)(32 * nb) * K + 32 * kb; c.ldw = N; c.ldt = K; c.valid = 1; return c;
.LBB0_635:
	s_cmp_gt_i32 s50, 0x17ffe
	s_cselect_b64 s[94:95], -1, 0
	s_mov_b64 s[10:11], -1
	s_and_b64 vcc, exec, s[94:95]
	s_cbranch_vccnz .LBB0_637
	s_add_i32 s3, s50, 1
	s_ashr_i32 s10, s3, 31
	s_lshr_b32 s10, s10, 25
	s_add_i32 s10, s3, s10
	s_ashr_i32 s11, s10, 7
	s_and_b32 s10, s10, 0xffffff80
	s_sub_i32 s15, s3, s10
	s_lshl_b32 s10, s11, 5
	s_add_i32 s11, s10, 0xffffd000
	s_cmp_lt_i32 s3, 0xc000
	s_cselect_b32 s3, s10, s11
	s_cselect_b32 s11, 0, 0x80
	s_lshl_b32 s14, s3, 1
	s_and_b32 s3, s3, 0x60
	s_and_b32 s14, s14, 0xffffff00
	s_or_b32 s3, s3, s11
	s_lshl_b32 s24, s15, 5
	v_readlane_b32 s52, v238, 28
	s_or_b32 s14, s3, s14
	s_ashr_i32 s25, s24, 31
	s_mul_i32 s15, s15, 0x300000
	v_readlane_b32 s56, v238, 32
	s_mul_hi_i32 s3, s24, 0x18000
	v_readlane_b32 s57, v238, 33
	s_add_u32 s15, s56, s15
	s_addc_u32 s3, s57, s3
	s_ashr_i32 s11, s10, 31
	s_lshl_b64 s[10:11], s[10:11], 2
	s_add_u32 s40, s15, s10
	s_addc_u32 s41, s3, s11
	s_ashr_i32 s15, s14, 31
	s_lshl_b64 s[10:11], s[14:15], 13
	s_add_u32 s3, s21, s10
	s_addc_u32 s14, s75, s11
	s_lshl_b64 s[10:11], s[24:25], 1
	s_add_u32 s92, s3, s10
	v_readlane_b32 s54, v238, 30
	s_addc_u32 s93, s14, s11
	s_lshl_b64 s[10:11], s[24:25], 2
	v_readlane_b32 s55, v238, 31
	s_add_u32 s34, s54, s10
	s_addc_u32 s35, s55, s11
	s_mov_b64 s[10:11], 0
	v_readlane_b32 s53, v238, 29
	v_readlane_b32 s58, v238, 34
	v_readlane_b32 s59, v238, 35
	v_readlane_b32 s60, v238, 36
	v_readlane_b32 s61, v238, 37
	v_readlane_b32 s62, v238, 38
	v_readlane_b32 s63, v238, 39
	v_readlane_b32 s64, v238, 40
	v_readlane_b32 s65, v238, 41
	v_readlane_b32 s66, v238, 42
	v_readlane_b32 s67, v238, 43
.LBB0_637:
	s_andn2_b64 vcc, exec, s[10:11]
	s_mov_b64 s[26:27], 0
	s_cbranch_vccnz .LBB0_641
	s_cmp_lt_u32 s50, 0x1c000
	s_cselect_b64 s[14:15], -1, 0
	s_and_b64 vcc, exec, s[14:15]
	s_cbranch_vccnz .LBB0_643
	v_readlane_b32 s52, v238, 28
	s_cmp_lt_u32 s50, 0x20000
	v_readlane_b32 s53, v238, 29
	v_readlane_b32 s54, v238, 30
	v_readlane_b32 s55, v238, 31
	v_readlane_b32 s56, v238, 32
	v_readlane_b32 s57, v238, 33
	s_mov_b32 s3, 0xfffe4000
	s_mov_b64 s[10:11], 0x20200000
	s_cselect_b64 s[14:15], -1, 0
	s_mov_b64 s[34:35], s[54:55]
	s_mov_b64 s[40:41], s[56:57]
	s_mov_b64 s[24:25], s[52:53]
	v_readlane_b32 s58, v238, 34
	v_readlane_b32 s59, v238, 35
	v_readlane_b32 s60, v238, 36
	v_readlane_b32 s61, v238, 37
	v_readlane_b32 s62, v238, 38
	v_readlane_b32 s63, v238, 39
	v_readlane_b32 s64, v238, 40
	v_readlane_b32 s65, v238, 41
	v_readlane_b32 s66, v238, 42
	v_readlane_b32 s67, v238, 43
	s_andn2_b64 vcc, exec, s[14:15]
	s_cbranch_vccz .LBB0_644

; __device__ __forceinline__ CvtTile cvt_decode(const Args& a, int t) {
;     ...
;     const float* W; bf16* WT; int KB, N, K;
;     if ((t -= CV_UP) < CV_PB) { W = a.in[15]; WT = (bf16*)(a.ws + WS_PB); KB = LW / 32; N = DM; K = LW; }
;     else if ((t -= CV_PB) < CV_WO) { W = a.in[16]; WT = (bf16*)(a.ws + WS_WOUT); KB = DM / 32; N = DM; K = DM; }
;     else return c;
;     const int kb = t % KB, nb = t / KB;
;     c.src = W + (size_t)(32 * kb) * N + 32 * nb; c.dst = WT + (size_t)(32 * nb) * K + 32 * kb; c.ldw = N; c.ldt = K; c.valid = 1; return c;
.LBB0_644:
	s_add_i32 s3, s50, s3
	s_add_i32 s3, s3, 1
	s_add_u32 s14, s44, s10
	s_addc_u32 s15, s45, s11
	s_lshl_b32 s10, s3, 5
	s_and_b32 s28, s10, 0xfe0
	s_lshl_b32 s10, s28, 14
	s_add_u32 s10, s24, s10
	s_addc_u32 s11, s25, 0
	s_lshr_b32 s3, s3, 2
	s_and_b32 s18, s3, 0x3fffffe0
	s_lshl_b32 s3, s18, 2
	s_add_u32 s40, s10, s3
	s_addc_u32 s41, s11, 0
	s_lshl_b64 s[10:11], s[18:19], 13
	s_add_u32 s3, s14, s10
	s_addc_u32 s10, s15, s11
	s_lshl_b32 s11, s28, 1
	v_readlane_b32 s52, v238, 28
	s_add_u32 s92, s3, s11
	v_readlane_b32 s54, v238, 30
	v_readlane_b32 s55, v238, 31
	s_addc_u32 s93, s10, 0
	s_mov_b64 s[96:97], 0x1000
	s_mov_b64 s[10:11], 0
	s_mov_b64 s[34:35], s[54:55]
	v_readlane_b32 s53, v238, 29
	v_readlane_b32 s56, v238, 32
	v_readlane_b32 s57, v238, 33
	v_readlane_b32 s58, v238, 34
	v_readlane_b32 s59, v238, 35
	v_readlane_b32 s60, v238, 36
	v_readlane_b32 s61, v238, 37
	v_readlane_b32 s62, v238, 38
	v_readlane_b32 s63, v238, 39
	v_readlane_b32 s64, v238, 40
	v_readlane_b32 s65, v238, 41
	v_readlane_b32 s66, v238, 42
	v_readlane_b32 s67, v238, 43

; #define LAS __attribute__((address_space(3)))
; #define LDS_BARRIER() do { asm volatile("s_waitcnt lgkmcnt(0)" ::: "memory"); __builtin_amdgcn_s_barrier(); asm volatile("" ::: "memory"); } while (0)
; __device__ __forceinline__ void cvt_issue(const CvtTile& c, f32x4 (&v)[4], f32x2c (&gl)[2], int lane) {
;     const float* p = c.src + (size_t)(2 * (lane >> 3)) * c.ldw + 4 * (lane & 7);
; #pragma unroll
;     for (int i = 0; i < 2; ++i)
; #pragma unroll
;         for (int h = 0; h < 2; ++h) v[2 * i + h] = __builtin_nontemporal_load((const f32x4*)(p + (size_t)(16 * i + h) * c.ldw));
; #pragma unroll
;     for (int i = 0; i < 2; ++i) gl[i] = *(const f32x2c*)(c.gain + 2 * (lane >> 3) + 16 * i);
; }
; __device__ __forceinline__ void mixer_b_unit(const Args& a, LAS unsigned char* lds, int unit) {
;     ...
;         cvt_issue(ctA, cvA, glA, lane); cvt_issue(ctB, cvB, glB, lane); cvt_issue(ctC, cvC, glC, lane);
;         LDS_BARRIER();
;         { f32x4 ca[2], cx[2];
; #pragma unroll
;           for (int m = 0; m < 2; ++m) { ca[m] = (f32x4){0.f, 0.f, 0.f, 0.f}; cx[m] = (f32x4){0.f, 0.f, 0.f, 0.f}; }
; #pragma unroll
;           for (int ks = 0; ks < 8; ++ks)
; #pragma unroll
;               for (int m = 0; m < 2; ++m) { const bf16x8 af = *(const LAS bf16x8*)(lds + MB_XC + (32 * rh + 16 * m + fr) * MB_XPITCH + (32 * ks + 8 * fq) * 2);
;                   const bf16x8 bxf = *(const LAS bf16x8*)(lds + MB_WX + (16 * cb + fr) * MB_XPITCH + (32 * ks + 8 * fq) * 2);
;                   ca[m] = __builtin_amdgcn_mfma_f32_16x16x32_bf16(bfa[ks], af, ca[m], 0, 0, 0); cx[m] = __builtin_amdgcn_mfma_f32_16x16x32_bf16(bxf, af, cx[m], 0, 0, 0); }
.LBB0_651:
	v_mul_u32_u24_e32 v2, s90, v138
	v_lshlrev_b32_e32 v2, 2, v2
	v_lshl_add_u64 v[66:67], s[30:31], 0, v[2:3]
	v_mov_b32_e32 v145, v3
	v_lshl_add_u64 v[66:67], v[66:67], 0, v[144:145]
	s_lshl_b32 s18, s90, 2
	global_load_dwordx4 v[90:93], v[66:67], off nt
	v_lshl_add_u64 v[66:67], v[66:67], 0, s[18:19]
	s_mul_i32 s30, s90, 60
	s_mov_b32 s31, s19
	global_load_dwordx4 v[110:113], v[66:67], off nt
	v_lshl_add_u64 v[66:67], v[66:67], 0, s[30:31]
	v_mul_u32_u24_e32 v2, s96, v138
	global_load_dwordx4 v[86:89], v[66:67], off nt
	v_lshl_add_u64 v[66:67], v[66:67], 0, s[18:19]
	v_lshlrev_b32_e32 v2, 2, v2
	global_load_dwordx4 v[102:105], v[66:67], off nt
	v_lshl_add_u64 v[66:67], s[40:41], 0, v[2:3]
	v_lshlrev_b32_e32 v68, 2, v138
	v_lshl_add_u64 v[66:67], v[66:67], 0, v[144:145]
	s_lshl_b32 s18, s96, 2
	global_load_dwordx2 v[152:153], v68, s[12:13]
	global_load_dwordx2 v[148:149], v68, s[12:13] offset:64
	global_load_dwordx4 v[78:81], v[66:67], off nt
	v_lshl_add_u64 v[66:67], v[66:67], 0, s[18:19]
	s_mul_i32 s12, s96, 60
	s_mov_b32 s13, s19
	global_load_dwordx4 v[106:109], v[66:67], off nt
	v_lshl_add_u64 v[66:67], v[66:67], 0, s[12:13]
	v_mul_u32_u24_e32 v2, s26, v138
	global_load_dwordx4 v[74:77], v[66:67], off nt
	v_lshl_add_u64 v[66:67], v[66:67], 0, s[18:19]
	v_lshlrev_b32_e32 v2, 2, v2
	global_load_dwordx4 v[98:101], v[66:67], off nt
	global_load_dwordx2 v[154:155], v68, s[34:35]
	global_load_dwordx2 v[150:151], v68, s[34:35] offset:64
	v_lshl_add_u64 v[66:67], s[38:39], 0, v[2:3]
	v_lshl_add_u64 v[66:67], v[66:67], 0, v[144:145]
	s_lshl_b64 s[12:13], s[26:27], 2
	global_load_dwordx4 v[70:73], v[66:67], off nt
	v_lshl_add_u64 v[66:67], v[66:67], 0, s[12:13]
	s_mul_i32 s18, s26, 60
	v_lshl_add_u64 v[82:83], v[66:67], 0, s[18:19]
	global_load_dwordx4 v[94:97], v[66:67], off nt
	s_mov_b32 s3, 0x3e800000
	global_load_dwordx4 v[66:69], v[82:83], off nt
	v_lshl_add_u64 v[82:83], v[82:83], 0, s[12:13]
	global_load_dwordx4 v[82:85], v[82:83], off nt
	s_waitcnt lgkmcnt(0)
	s_barrier
	ds_read_b128 v[114:117], v163
	ds_read_b128 v[118:121], v164
	ds_read_b128 v[182:185], v164 offset:8448
	s_waitcnt lgkmcnt(1)
	v_mfma_f32_16x16x32_bf16 v[178:181], v[6:9], v[118:121], 0
	s_mov_b32 s12, 0x3e2aaaab
	v_mfma_f32_16x16x32_bf16 v[118:121], v[114:117], v[118:121], 0
	s_waitcnt lgkmcnt(0)
	v_mfma_f32_16x16x32_bf16 v[186:189], v[6:9], v[182:185], 0
	v_mfma_f32_16x16x32_bf16 v[114:117], v[114:117], v[182:185], 0
	ds_read_b128 v[182:185], v163 offset:64
	ds_read_b128 v[190:193], v164 offset:64
	s_waitcnt lgkmcnt(0)
	v_mfma_f32_16x16x32_bf16 v[178:181], v[10:13], v[190:193], v[178:181]
	v_mfma_f32_16x16x32_bf16 v[118:121], v[182:185], v[190:193], v[118:121]
	ds_read_b128 v[190:193], v164 offset:8512
	s_waitcnt lgkmcnt(0)
	v_mfma_f32_16x16x32_bf16 v[186:189], v[10:13], v[190:193], v[186:189]
	v_mfma_f32_16x16x32_bf16 v[114:117], v[182:185], v[190:193], v[114:117]
	ds_read_b128 v[182:185], v163 offset:128
	ds_read_b128 v[190:193], v164 offset:128
	s_waitcnt lgkmcnt(0)
	v_mfma_f32_16x16x32_bf16 v[178:181], v[14:17], v[190:193], v[178:181]
	v_mfma_f32_16x16x32_bf16 v[118:121], v[182:185], v[190:193], v[118:121]
	ds_read_b128 v[190:193], v164 offset:8576
	s_waitcnt lgkmcnt(0)
	v_mfma_f32_16x16x32_bf16 v[186:189], v[14:17], v[190:193], v[186:189]
	v_mfma_f32_16x16x32_bf16 v[114:117], v[182:185], v[190:193], v[114:117]
	ds_read_b128 v[182:185], v163 offset:192
	ds_read_b128 v[190:193], v164 offset:192
	s_waitcnt lgkmcnt(0)
	v_mfma_f32_16x16x32_bf16 v[178:181], v[18:21], v[190:193], v[178:181]
	v_mfma_f32_16x16x32_bf16 v[118:121], v[182:185], v[190:193], v[118:121]
	ds_read_b128 v[190:193], v164 offset:8640
	s_waitcnt lgkmcnt(0)
	v_mfma_f32_16x16x32_bf16 v[186:189], v[18:21], v[190:193], v[186:189]
	v_mfma_f32_16x16x32_bf16 v[114:117], v[182:185], v[190:193], v[114:117]
	ds_read_b128 v[182:185], v163 offset:256
	ds_read_b128 v[190:193], v164 offset:256
	s_waitcnt lgkmcnt(0)
	v_mfma_f32_16x16x32_bf16 v[178:181], v[22:25], v[190:193], v[178:181]
	v_mfma_f32_16x16x32_bf16 v[118:121], v[182:185], v[190:193], v[118:121]
	ds_read_b128 v[190:193], v164 offset:8704
	s_waitcnt lgkmcnt(0)
	v_mfma_f32_16x16x32_bf16 v[186:189], v[22:25], v[190:193], v[186:189]
	v_mfma_f32_16x16x32_bf16 v[114:117], v[182:185], v[190:193], v[114:117]
	ds_read_b128 v[182:185], v163 offset:320
	ds_read_b128 v[190:193], v164 offset:320
	s_waitcnt lgkmcnt(0)
	v_mfma_f32_16x16x32_bf16 v[178:181], v[26:29], v[190:193], v[178:181]
	v_mfma_f32_16x16x32_bf16 v[118:121], v[182:185], v[190:193], v[118:121]
	ds_read_b128 v[190:193], v164 offset:8768
	s_waitcnt lgkmcnt(0)
	v_mfma_f32_16x16x32_bf16 v[186:189], v[26:29], v[190:193], v[186:189]
	v_mfma_f32_16x16x32_bf16 v[114:117], v[182:185], v[190:193], v[114:117]
	ds_read_b128 v[182:185], v163 offset:384
	ds_read_b128 v[190:193], v164 offset:384
	s_waitcnt lgkmcnt(0)
	v_mfma_f32_16x16x32_bf16 v[178:181], v[30:33], v[190:193], v[178:181]
	v_mfma_f32_16x16x32_bf16 v[118:121], v[182:185], v[190:193], v[118:121]
	ds_read_b128 v[190:193], v164 offset:8832
	s_waitcnt lgkmcnt(0)
	v_mfma_f32_16x16x32_bf16 v[186:189], v[30:33], v[190:193], v[186:189]
	v_mfma_f32_16x16x32_bf16 v[182:185], v[182:185], v[190:193], v[114:117]
	ds_read_b128 v[190:193], v163 offset:448
	s_nop 1
	ds_read_b128 v[114:117], v164 offset:448
	s_waitcnt lgkmcnt(0)
	v_mfma_f32_16x16x32_bf16 v[178:181], v[34:37], v[114:117], v[178:181]
	v_mfma_f32_16x16x32_bf16 v[194:197], v[190:193], v[114:117], v[118:121]
	s_nop 6
	v_fma_f32 v178, -v178, s74, v4
	v_fma_f32 v179, -v179, s74, v5
	v_exp_f32_e32 v178, v178
	v_exp_f32_e32 v179, v179
	ds_read_b128 v[118:121], v164 offset:8896
	s_waitcnt lgkmcnt(0)
; __device__ __forceinline__ float bf_lo(unsigned w) { return __uint_as_float(w << 16); }
; __device__ __forceinline__ float bf_hi(unsigned w) { return __uint_as_float(w & 0xffff0000u); }
; #define LAS __attribute__((address_space(3)))
; #define LDS_BARRIER() do { asm volatile("s_waitcnt lgkmcnt(0)" ::: "memory"); __builtin_amdgcn_s_barrier(); asm volatile("" ::: "memory"); } while (0)
; __device__ __forceinline__ void mixer_b_unit(const Args& a, LAS unsigned char* lds, int unit) {
;     ...
; #pragma unroll
;           for (int m = 0; m < 2; ++m) { const int r = 32 * rh + 16 * m + fr; const int cl = 16 * cb + 4 * fq;
;               const u32x2 xw = *(const LAS u32x2*)(lds + MB_XC + r * MB_XPITCH + (64 * q + cl) * 2);
;               const unsigned xwd[2] = {xw.x, xw.y};
; #pragma unroll
;               for (int p = 0; p < 2; ++p) {
;                   const f32x2 ta = (f32x2){ca[m][2 * p], ca[m][2 * p + 1]} * -1.4426950409f + ba2[p], tx = (f32x2){cx[m][2 * p], cx[m][2 * p + 1]} * -1.4426950409f + bx2[p];
;                   f32x2 da, dx; da.x = __builtin_amdgcn_exp2f(ta.x); da.y = __builtin_amdgcn_exp2f(ta.y); dx.x = __builtin_amdgcn_exp2f(tx.x); dx.y = __builtin_amdgcn_exp2f(tx.y);
;                   da = da + 1.0f; dx = dx + 1.0f;
;                   f32x2 rgt, ig; rgt.x = __builtin_amdgcn_rcpf(da.x); rgt.y = __builtin_amdgcn_rcpf(da.y); ig.x = __builtin_amdgcn_rcpf(dx.x); ig.y = __builtin_amdgcn_rcpf(dx.y);
;                   const f32x2 l2 = rgt * spl2[p], y = rgt * spy2[p];
;                   f32x2 av; av.x = __builtin_amdgcn_exp2f(l2.x); av.y = __builtin_amdgcn_exp2f(l2.y);
;                   f32x2 ser = y * 0.041666668f + 0.16666667f; ser = ser * y + 0.5f; ser = ser * y + 1.0f; ser = ser * (-y);
;                   f32x2 dir = 1.0f - av * av;
;                   asm volatile("" : "+v"(ser), "+v"(dir));
;                   f32x2 om; om.x = (y.x > -0.0625f) ? ser.x : dir.x; om.y = (y.y > -0.0625f) ? ser.y : dir.y;
;                   f32x2 sq; sq.x = __builtin_amdgcn_sqrtf(om.x); sq.y = __builtin_amdgcn_sqrtf(om.y);
;                   const f32x2 gx = sq * ig * (f32x2){bf_lo(xwd[p]), bf_hi(xwd[p])};
;                   ag[r * 65 + cl + 2 * p] = (f32x2){av.x, gx.x}; ag[r * 65 + cl + 2 * p + 1] = (f32x2){av.y, gx.y}; } } }
;         LDS_BARRIER();
	v_mfma_f32_16x16x32_bf16 v[114:117], v[34:37], v[118:121], v[186:189]
	v_add_f32_e64 v178, v178, 1.0
	v_add_f32_e64 v179, v179, 1.0
	s_nop 0
	v_mov_b64_e32 v[188:189], s[12:13]
	v_rcp_f32_e32 v178, v178
	v_rcp_f32_e32 v179, v179
	v_mfma_f32_16x16x32_bf16 v[118:121], v[190:193], v[118:121], v[182:185]
	s_nop 0
	v_fma_f32 v114, -v114, s74, v4
	v_fma_f32 v115, -v115, s74, v5
	v_pk_mul_f32 v[186:187], v[128:129], v[178:179]
	v_pk_mul_f32 v[178:179], v[126:127], v[178:179]
	v_exp_f32_e32 v186, v186
	v_exp_f32_e32 v187, v187
	v_pk_fma_f32 v[184:185], v[194:195], s[74:75], v[124:125] op_sel_hi:[1,0,1] neg_lo:[1,0,0] neg_hi:[1,0,0]
	v_pk_fma_f32 v[190:191], v[178:179], s[84:85], v[188:189] op_sel_hi:[1,0,0]
	v_exp_f32_e32 v184, v184
	v_exp_f32_e32 v185, v185
	v_pk_fma_f32 v[190:191], v[178:179], v[190:191], 0.5 op_sel_hi:[1,1,0]
	v_pk_fma_f32 v[192:193], v[186:187], v[186:187], 1.0 op_sel_hi:[1,1,0] neg_lo:[1,0,0] neg_hi:[1,0,0]
	v_pk_fma_f32 v[190:191], v[178:179], v[190:191], 1.0 op_sel_hi:[1,1,0]
	v_cmp_lt_f32_e32 vcc, s43, v178
	v_pk_mul_f32 v[190:191], v[190:191], v[178:179] neg_lo:[0,1] neg_hi:[0,1]
	ds_read_b64 v[182:183], v165
	v_pk_add_f32 v[184:185], v[184:185], 1.0 op_sel_hi:[1,0]
	v_cndmask_b32_e32 v2, v192, v190, vcc
	v_cmp_lt_f32_e32 vcc, s43, v179
	v_rcp_f32_e32 v184, v184
	v_rcp_f32_e32 v185, v185
	v_cndmask_b32_e32 v145, v193, v191, vcc
	v_sqrt_f32_e32 v178, v2
	v_sqrt_f32_e32 v179, v145
	v_add_u32_e32 v2, 0x8400, v166
	v_exp_f32_e32 v114, v114
	v_exp_f32_e32 v115, v115
	v_pk_mul_f32 v[178:179], v[184:185], v[178:179]
	s_waitcnt lgkmcnt(0)
	v_lshlrev_b32_e32 v184, 16, v182
	v_and_b32_e32 v185, 0xffff0000, v182
	v_pk_mul_f32 v[178:179], v[178:179], v[184:185]
	v_mov_b32_e32 v184, v186
	v_mov_b32_e32 v185, v178
	v_mov_b32_e32 v178, v187
	ds_write2_b64 v2, v[184:185], v[178:179] offset1:1
	v_pk_fma_f32 v[178:179], v[180:181], s[74:75], v[130:131] op_sel_hi:[1,0,1] neg_lo:[1,0,0] neg_hi:[1,0,0]
	v_pk_fma_f32 v[180:181], v[196:197], s[74:75], v[132:133] op_sel_hi:[1,0,1] neg_lo:[1,0,0] neg_hi:[1,0,0]
	v_exp_f32_e32 v178, v178
	v_exp_f32_e32 v179, v179
	v_exp_f32_e32 v180, v180
	v_exp_f32_e32 v181, v181
	v_pk_add_f32 v[114:115], v[114:115], 1.0 op_sel_hi:[1,0]
	v_pk_add_f32 v[178:179], v[178:179], 1.0 op_sel_hi:[1,0]
	v_rcp_f32_e32 v114, v114
	v_rcp_f32_e32 v178, v178
	v_rcp_f32_e32 v179, v179
	v_pk_add_f32 v[180:181], v[180:181], 1.0 op_sel_hi:[1,0]
	v_rcp_f32_e32 v115, v115
	v_rcp_f32_e32 v180, v180
	v_pk_mul_f32 v[184:185], v[136:137], v[178:179]
	v_pk_mul_f32 v[178:179], v[134:135], v[178:179]
	v_exp_f32_e32 v184, v184
	v_exp_f32_e32 v185, v185
	v_pk_fma_f32 v[186:187], v[178:179], s[84:85], v[188:189] op_sel_hi:[1,0,0]
	v_cmp_lt_f32_e32 vcc, s43, v178
	v_pk_fma_f32 v[186:187], v[178:179], v[186:187], 0.5 op_sel_hi:[1,1,0]
	v_pk_fma_f32 v[190:191], v[184:185], v[184:185], 1.0 op_sel_hi:[1,1,0] neg_lo:[1,0,0] neg_hi:[1,0,0]
	v_pk_fma_f32 v[186:187], v[178:179], v[186:187], 1.0 op_sel_hi:[1,1,0]
	v_rcp_f32_e32 v181, v181
	v_pk_mul_f32 v[186:187], v[186:187], v[178:179] neg_lo:[0,1] neg_hi:[0,1]
	v_pk_fma_f32 v[118:119], v[118:119], s[74:75], v[124:125] op_sel_hi:[1,0,1] neg_lo:[1,0,0] neg_hi:[1,0,0]
	s_nop 0
	v_cndmask_b32_e32 v2, v190, v186, vcc
	v_cmp_lt_f32_e32 vcc, s43, v179
	v_sqrt_f32_e32 v178, v2
	v_add_u32_e32 v2, 0x8410, v166
	v_cndmask_b32_e32 v145, v191, v187, vcc
	v_sqrt_f32_e32 v179, v145
	v_exp_f32_e32 v118, v118
	v_exp_f32_e32 v119, v119
	v_pk_mul_f32 v[178:179], v[180:181], v[178:179]
	v_lshlrev_b32_e32 v180, 16, v183
	v_and_b32_e32 v181, 0xffff0000, v183
	v_pk_mul_f32 v[178:179], v[178:179], v[180:181]
	v_mov_b32_e32 v180, v184
	v_mov_b32_e32 v181, v178
	v_mov_b32_e32 v178, v185
	ds_write2_b64 v2, v[180:181], v[178:179] offset1:1
	v_pk_mul_f32 v[180:181], v[128:129], v[114:115]
	v_pk_mul_f32 v[114:115], v[126:127], v[114:115]
	v_exp_f32_e32 v180, v180
	v_exp_f32_e32 v181, v181
	v_pk_fma_f32 v[182:183], v[114:115], s[84:85], v[188:189] op_sel_hi:[1,0,0]
	v_cmp_lt_f32_e32 vcc, s43, v114
	v_pk_fma_f32 v[182:183], v[114:115], v[182:183], 0.5 op_sel_hi:[1,1,0]
	v_pk_fma_f32 v[184:185], v[180:181], v[180:181], 1.0 op_sel_hi:[1,1,0] neg_lo:[1,0,0] neg_hi:[1,0,0]
	v_pk_fma_f32 v[182:183], v[114:115], v[182:183], 1.0 op_sel_hi:[1,1,0]
	ds_read_b64 v[178:179], v165 offset:8448
	v_pk_mul_f32 v[182:183], v[182:183], v[114:115] neg_lo:[0,1] neg_hi:[0,1]
	v_pk_add_f32 v[118:119], v[118:119], 1.0 op_sel_hi:[1,0]
	s_nop 0
	v_cndmask_b32_e32 v2, v184, v182, vcc
	v_cmp_lt_f32_e32 vcc, s43, v115
	v_rcp_f32_e32 v118, v118
	v_rcp_f32_e32 v119, v119
	v_cndmask_b32_e32 v115, v185, v183, vcc
	v_sqrt_f32_e32 v114, v2
	v_sqrt_f32_e32 v115, v115
	v_add_u32_e32 v2, 0xa480, v166
	v_pk_mul_f32 v[114:115], v[118:119], v[114:115]
	s_waitcnt lgkmcnt(0)
	v_lshlrev_b32_e32 v118, 16, v178
	v_and_b32_e32 v119, 0xffff0000, v178
	v_pk_mul_f32 v[114:115], v[114:115], v[118:119]
	v_mov_b32_e32 v118, v180
	v_mov_b32_e32 v119, v114
	v_mov_b32_e32 v114, v181
	ds_write2_b64 v2, v[118:119], v[114:115] offset1:1
	v_pk_fma_f32 v[114:115], v[116:117], s[74:75], v[130:131] op_sel_hi:[1,0,1] neg_lo:[1,0,0] neg_hi:[1,0,0]
	v_pk_fma_f32 v[116:117], v[120:121], s[74:75], v[132:133] op_sel_hi:[1,0,1] neg_lo:[1,0,0] neg_hi:[1,0,0]
	v_exp_f32_e32 v114, v114
	v_exp_f32_e32 v115, v115
	v_exp_f32_e32 v116, v116
	v_exp_f32_e32 v117, v117
	v_pk_add_f32 v[114:115], v[114:115], 1.0 op_sel_hi:[1,0]
	s_nop 0
	v_rcp_f32_e32 v114, v114
	v_rcp_f32_e32 v115, v115
	v_pk_add_f32 v[116:117], v[116:117], 1.0 op_sel_hi:[1,0]
	v_pk_mul_f32 v[118:119], v[136:137], v[114:115]
	v_pk_mul_f32 v[114:115], v[134:135], v[114:115]
	v_exp_f32_e32 v118, v118
	v_exp_f32_e32 v119, v119
	v_pk_fma_f32 v[120:121], v[114:115], s[84:85], v[188:189] op_sel_hi:[1,0,0]
	v_cmp_lt_f32_e32 vcc, s43, v114
	v_pk_fma_f32 v[120:121], v[114:115], v[120:121], 0.5 op_sel_hi:[1,1,0]
	v_pk_fma_f32 v[180:181], v[118:119], v[118:119], 1.0 op_sel_hi:[1,1,0] neg_lo:[1,0,0] neg_hi:[1,0,0]
	v_pk_fma_f32 v[120:121], v[114:115], v[120:121], 1.0 op_sel_hi:[1,1,0]
	v_rcp_f32_e32 v116, v116
	v_pk_mul_f32 v[120:121], v[120:121], v[114:115] neg_lo:[0,1] neg_hi:[0,1]
	v_rcp_f32_e32 v117, v117
	s_nop 0
	v_cndmask_b32_e32 v2, v180, v120, vcc
	v_cmp_lt_f32_e32 vcc, s43, v115
	v_sqrt_f32_e32 v114, v2
	v_add_u32_e32 v2, 0xa490, v166
	v_cndmask_b32_e32 v115, v181, v121, vcc
	v_sqrt_f32_e32 v115, v115
	v_add_u32_e32 v120, -8, v141
	v_pk_mul_f32 v[114:115], v[116:117], v[114:115]
	v_lshlrev_b32_e32 v116, 16, v179
	v_and_b32_e32 v117, 0xffff0000, v179
	v_pk_mul_f32 v[114:115], v[114:115], v[116:117]
	v_mov_b32_e32 v116, v118
	v_mov_b32_e32 v117, v114
	v_mov_b32_e32 v114, v119
	ds_write2_b64 v2, v[116:117], v[114:115] offset1:1
	s_waitcnt lgkmcnt(0)
	s_barrier
; __device__ __forceinline__ unsigned cvt_pk_bf16(float lo, float hi) { unsigned r; asm volatile("v_cvt_pk_bf16_f32 %0, %1, %2" : "=v"(r) : "v"(lo), "v"(hi)); return r; }
; #define LAS __attribute__((address_space(3)))
; __device__ __forceinline__ void cvt_write(const CvtTile& c, const f32x4 (&v)[4], const f32x2c (&gl)[2], LAS unsigned* scr, int lane) {
;     if (c.valid) { const int n4 = 4 * (lane & 7), kq = lane >> 3;
; #pragma unroll
;         for (int i = 0; i < 2; ++i) { const float g0 = c.has_gain ? gl[i].x : 1.0f, g1 = c.has_gain ? gl[i].y : 1.0f;
; #pragma unroll
;             for (int j = 0; j < 4; ++j) scr[(n4 + j) * 17 + kq + 8 * i] = cvt_pk_bf16(v[2 * i][j] * g0, v[2 * i + 1][j] * g1); } }
; }
; __device__ __forceinline__ void mixer_b_unit(const Args& a, LAS unsigned char* lds, int unit) {
;     ...
;         { f32x2 v[8]; float P = 1.f, Hh = 0.f;
; #pragma unroll
;           for (int i = 0; i < 8; ++i) { v[i] = ag[(8 * rgp + i) * 65 + 8 * wave + c8]; Hh = v[i].x * Hh + v[i].y; P *= v[i].x; }
; #pragma unroll
;           for (int d = 8; d < 64; d <<= 1) { const float Pp = __shfl_up(P, d), Hp = __shfl_up(Hh, d); if (lane >= d) { Hh = P * Hp + Hh; P = P * Pp; } }
;           const float Pe = __shfl_up(P, 8), He = __shfl_up(Hh, 8);
;           float c = (rgp == 0) ? carry : (Pe * carry + He);
;           const float Pt = __shfl(P, 56 + c8), Ht = __shfl(Hh, 56 + c8);
;           carry = Pt * carry + Ht;
; #pragma unroll
;           for (int i = 0; i < 8; ++i) { c = v[i].x * c + v[i].y; const float y = c * __uint_as_float((unsigned)yr[i] << 16); YB[gb + (size_t)i * LW] = (bf16)(cvt_pk_bf16(y, 0.f) & 0xffffu); } }
	v_add_u32_e32 v2, 0x8000, v167
	ds_read2_b64 v[116:119], v2 offset0:128 offset1:193
	v_add_u32_e32 v114, 0x8800, v167
	ds_read2_b64 v[178:181], v114 offset0:2 offset1:67
	ds_read2_b64 v[182:185], v114 offset0:132 offset1:197
	v_add_u32_e32 v114, 0x9000, v167
	s_waitcnt lgkmcnt(2)
	v_fma_f32 v2, 0, v116, v117
	ds_read2_b64 v[186:189], v114 offset0:6 offset1:71
	v_mul_f32_e32 v114, v116, v118
	v_fma_f32 v2, v118, v2, v119
	s_waitcnt lgkmcnt(2)
	v_mul_f32_e32 v114, v114, v178
	v_fma_f32 v2, v178, v2, v179
	v_mul_f32_e32 v114, v114, v180
	v_fma_f32 v2, v180, v2, v181
	s_waitcnt lgkmcnt(1)
	v_mul_f32_e32 v114, v114, v182
	v_and_b32_e32 v115, 64, v141
	v_fma_f32 v2, v182, v2, v183
	v_mul_f32_e32 v114, v114, v184
	v_cmp_lt_i32_e32 vcc, v120, v115
	v_fma_f32 v2, v184, v2, v185
	s_waitcnt lgkmcnt(0)
	v_mul_f32_e32 v114, v114, v186
	v_cndmask_b32_e32 v120, v120, v141, vcc
	v_fma_f32 v2, v186, v2, v187
	v_mul_f32_e32 v114, v114, v188
	v_lshlrev_b32_e32 v120, 2, v120
	v_fma_f32 v2, v188, v2, v189
	ds_bpermute_b32 v121, v120, v114
	ds_bpermute_b32 v145, v120, v2
	s_waitcnt lgkmcnt(1)
	v_mul_f32_e32 v121, v114, v121
	s_waitcnt lgkmcnt(0)
	v_fma_f32 v145, v114, v145, v2
	v_cndmask_b32_e64 v114, v121, v114, s[0:1]
	v_add_u32_e32 v121, -16, v141
	v_cmp_lt_i32_e32 vcc, v121, v115
	v_cndmask_b32_e64 v2, v145, v2, s[0:1]
	s_nop 0
	v_cndmask_b32_e32 v121, v121, v141, vcc
	v_lshlrev_b32_e32 v121, 2, v121
	ds_bpermute_b32 v145, v121, v114
	ds_bpermute_b32 v121, v121, v2
	s_waitcnt lgkmcnt(1)
	v_mul_f32_e32 v145, v114, v145
	s_waitcnt lgkmcnt(0)
	v_fma_f32 v121, v114, v121, v2
	v_cndmask_b32_e64 v2, v121, v2, s[4:5]
	v_subrev_u32_e32 v121, 32, v141
	v_cmp_lt_i32_e32 vcc, v121, v115
	v_cndmask_b32_e64 v114, v145, v114, s[4:5]
	v_or_b32_e32 v115, v115, v157
	v_cndmask_b32_e32 v121, v121, v141, vcc
	v_lshlrev_b32_e32 v121, 2, v121
	ds_bpermute_b32 v145, v121, v114
	ds_bpermute_b32 v121, v121, v2
	s_waitcnt lgkmcnt(1)
	v_mul_f32_e32 v145, v114, v145
	s_waitcnt lgkmcnt(0)
	v_fma_f32 v121, v114, v121, v2
	v_cndmask_b32_e64 v114, v145, v114, s[6:7]
	v_cndmask_b32_e64 v2, v121, v2, s[6:7]
	ds_bpermute_b32 v121, v120, v114
	ds_bpermute_b32 v120, v120, v2
	s_waitcnt lgkmcnt(0)
	v_fmac_f32_e32 v120, v156, v121
	v_cndmask_b32_e64 v120, v120, v156, s[0:1]
	v_lshlrev_b32_e32 v121, 2, v115
	ds_bpermute_b32 v115, v121, v114 offset:224
	ds_bpermute_b32 v114, v121, v2 offset:224
	v_fma_f32 v2, v116, v120, v117
	s_waitcnt vmcnt(30)
	v_lshlrev_b32_e32 v116, 16, v176
	v_mul_f32_e32 v116, v2, v116
	v_cvt_pk_bf16_f32 v120, v116, v3
	v_add_co_u32_e32 v116, vcc, s3, v146
	v_fmac_f32_e32 v119, v118, v2
	s_nop 0
	v_addc_co_u32_e32 v117, vcc, 0, v147, vcc
	s_waitcnt vmcnt(29)
	v_lshlrev_b32_e32 v2, 16, v175
	s_mov_b32 s3, 0x3e802000
	global_store_short v[116:117], v120, off
	v_mul_f32_e32 v2, v119, v2
	v_add_co_u32_e32 v116, vcc, s3, v146
	v_cvt_pk_bf16_f32 v2, v2, v3
	s_mov_b32 s3, 0x3e804000
	s_nop 0
	v_addc_co_u32_e32 v117, vcc, 0, v147, vcc
	global_store_short v[116:117], v2, off
	v_fma_f32 v2, v178, v119, v179
	s_waitcnt vmcnt(30)
	v_lshlrev_b32_e32 v116, 16, v174
	v_mul_f32_e32 v116, v2, v116
	v_cvt_pk_bf16_f32 v118, v116, v3
	v_add_co_u32_e32 v116, vcc, s3, v146
	v_fmac_f32_e32 v181, v180, v2
	s_nop 0
	v_addc_co_u32_e32 v117, vcc, 0, v147, vcc
	s_waitcnt vmcnt(29)
	v_lshlrev_b32_e32 v2, 16, v173
	s_mov_b32 s3, 0x3e806000
	global_store_short v[116:117], v118, off
	v_mul_f32_e32 v2, v181, v2
	v_add_co_u32_e32 v116, vcc, s3, v146
	v_cvt_pk_bf16_f32 v2, v2, v3
	s_mov_b32 s3, 0x3e808000
	s_nop 0
	v_addc_co_u32_e32 v117, vcc, 0, v147, vcc
	global_store_short v[116:117], v2, off
	v_fma_f32 v2, v182, v181, v183
	s_waitcnt vmcnt(30)
	v_lshlrev_b32_e32 v116, 16, v172
	v_mul_f32_e32 v116, v2, v116
	v_cvt_pk_bf16_f32 v118, v116, v3
	v_add_co_u32_e32 v116, vcc, s3, v146
	v_fmac_f32_e32 v185, v184, v2
	s_nop 0
	v_addc_co_u32_e32 v117, vcc, 0, v147, vcc
	s_waitcnt vmcnt(29)
	v_lshlrev_b32_e32 v2, 16, v171
	s_mov_b32 s3, 0x3e80a000
	global_store_short v[116:117], v118, off
	v_mul_f32_e32 v2, v185, v2
	v_add_co_u32_e32 v116, vcc, s3, v146
	v_cvt_pk_bf16_f32 v2, v2, v3
	s_nop 1
	v_addc_co_u32_e32 v117, vcc, 0, v147, vcc
	global_store_short v[116:117], v2, off
	v_fma_f32 v2, v186, v185, v187
	s_waitcnt vmcnt(30)
	v_lshlrev_b32_e32 v116, 16, v170
	v_mul_f32_e32 v116, v2, v116
	v_cvt_pk_bf16_f32 v118, v116, v3
	v_add_co_u32_e32 v116, vcc, 0x3e80c000, v146
	v_fmac_f32_e32 v189, v188, v2
	s_nop 0
	v_addc_co_u32_e32 v117, vcc, 0, v147, vcc
	s_waitcnt vmcnt(29)
	v_lshlrev_b32_e32 v2, 16, v177
	global_store_short v[116:117], v118, off
	v_mul_f32_e32 v2, v189, v2
	v_add_co_u32_e32 v116, vcc, 0x3e80e000, v146
	v_cvt_pk_bf16_f32 v2, v2, v3
	s_nop 1
	v_addc_co_u32_e32 v117, vcc, 0, v147, vcc
	global_store_short v[116:117], v2, off
	v_cndmask_b32_e64 v2, 0, 1, s[24:25]
	v_cmp_ne_u32_e64 s[12:13], 1, v2
	s_andn2_b64 vcc, exec, s[24:25]
	s_cbranch_vccnz .LBB0_653
	s_waitcnt vmcnt(19)
	v_cndmask_b32_e64 v2, v152, 1.0, s[8:9]
	v_cndmask_b32_e64 v116, v153, 1.0, s[8:9]
	v_mul_f32_e32 v90, v90, v2
	v_mul_f32_e32 v110, v110, v116
	v_cvt_pk_bf16_f32 v90, v90, v110
	ds_write_b32 v168, v90
	v_mul_f32_e32 v90, v91, v2
	v_mul_f32_e32 v91, v111, v116
	v_cvt_pk_bf16_f32 v90, v90, v91
	ds_write_b32 v168, v90 offset:68
	v_mul_f32_e32 v90, v92, v2
	v_mul_f32_e32 v91, v112, v116
	v_cvt_pk_bf16_f32 v90, v90, v91
	v_mul_f32_e32 v2, v93, v2
	ds_write_b32 v168, v90 offset:136
	v_mul_f32_e32 v90, v113, v116
	v_cvt_pk_bf16_f32 v2, v2, v90
	ds_write_b32 v168, v2 offset:204
	s_waitcnt vmcnt(18)
	v_cndmask_b32_e64 v2, v148, 1.0, s[8:9]
	v_cndmask_b32_e64 v90, v149, 1.0, s[8:9]
	v_mul_f32_e32 v86, v86, v2
	v_mul_f32_e32 v91, v102, v90
	v_cvt_pk_bf16_f32 v86, v86, v91
	ds_write_b32 v168, v86 offset:32
	v_mul_f32_e32 v86, v87, v2
	v_mul_f32_e32 v87, v103, v90
	v_cvt_pk_bf16_f32 v86, v86, v87
	ds_write_b32 v168, v86 offset:100
	v_mul_f32_e32 v86, v88, v2
	v_mul_f32_e32 v87, v104, v90
	v_cvt_pk_bf16_f32 v86, v86, v87
	v_mul_f32_e32 v2, v89, v2
	ds_write_b32 v168, v86 offset:168
	v_mul_f32_e32 v86, v105, v90
	v_cvt_pk_bf16_f32 v2, v2, v86
	ds_write_b32 v168, v2 offset:236
; __device__ __forceinline__ unsigned cvt_pk_bf16(float lo, float hi) { unsigned r; asm volatile("v_cvt_pk_bf16_f32 %0, %1, %2" : "=v"(r) : "v"(lo), "v"(hi)); return r; }
; #define LAS __attribute__((address_space(3)))
; __device__ __forceinline__ void cvt_write(const CvtTile& c, const f32x4 (&v)[4], const f32x2c (&gl)[2], LAS unsigned* scr, int lane) {
;     if (c.valid) { const int n4 = 4 * (lane & 7), kq = lane >> 3;
; #pragma unroll
;         for (int i = 0; i < 2; ++i) { const float g0 = c.has_gain ? gl[i].x : 1.0f, g1 = c.has_gain ? gl[i].y : 1.0f;
; #pragma unroll
;             for (int j = 0; j < 4; ++j) scr[(n4 + j) * 17 + kq + 8 * i] = cvt_pk_bf16(v[2 * i][j] * g0, v[2 * i + 1][j] * g1); } }
; }
; __device__ __forceinline__ void mixer_b_unit(const Args& a, LAS unsigned char* lds, int unit) {
;     ...
;         cvt_write(ctA, cvA, glA, cscr, lane); cvt_write(ctB, cvB, glB, cscr + 32 * 17, lane); cvt_write(ctC, cvC, glC, cscr + 64 * 17, lane); asm volatile("" ::: "memory");
.LBB0_653:
	s_xor_b64 s[8:9], s[10:11], -1
	v_cndmask_b32_e64 v2, 0, 1, s[8:9]
	v_cmp_ne_u32_e64 s[10:11], 1, v2
	s_andn2_b64 vcc, exec, s[8:9]
	s_cbranch_vccnz .LBB0_655
	s_waitcnt vmcnt(13)
	v_cndmask_b32_e64 v2, v154, 1.0, s[94:95]
	v_cndmask_b32_e64 v86, v155, 1.0, s[94:95]
	v_mul_f32_e32 v78, v78, v2
	v_mul_f32_e32 v87, v106, v86
	v_cvt_pk_bf16_f32 v78, v78, v87
	ds_write_b32 v168, v78 offset:2176
	v_mul_f32_e32 v78, v79, v2
	v_mul_f32_e32 v79, v107, v86
	v_cvt_pk_bf16_f32 v78, v78, v79
	ds_write_b32 v168, v78 offset:2244
	v_mul_f32_e32 v78, v80, v2
	v_mul_f32_e32 v79, v108, v86
	v_cvt_pk_bf16_f32 v78, v78, v79
	v_mul_f32_e32 v2, v81, v2
	ds_write_b32 v168, v78 offset:2312
	v_mul_f32_e32 v78, v109, v86
	v_cvt_pk_bf16_f32 v2, v2, v78
	ds_write_b32 v168, v2 offset:2380
	s_waitcnt vmcnt(12)
	v_cndmask_b32_e64 v2, v150, 1.0, s[94:95]
	v_cndmask_b32_e64 v78, v151, 1.0, s[94:95]
	v_mul_f32_e32 v74, v74, v2
	v_mul_f32_e32 v79, v98, v78
	v_cvt_pk_bf16_f32 v74, v74, v79
	ds_write_b32 v168, v74 offset:2208
	v_mul_f32_e32 v74, v75, v2
	v_mul_f32_e32 v75, v99, v78
	v_cvt_pk_bf16_f32 v74, v74, v75
	ds_write_b32 v168, v74 offset:2276
	v_mul_f32_e32 v74, v76, v2
	v_mul_f32_e32 v75, v100, v78
	v_cvt_pk_bf16_f32 v74, v74, v75
	v_mul_f32_e32 v2, v77, v2
	ds_write_b32 v168, v74 offset:2344
	v_mul_f32_e32 v74, v101, v78
	v_cvt_pk_bf16_f32 v2, v2, v74
	ds_write_b32 v168, v2 offset:2412
.LBB0_655:
	s_xor_b64 s[16:17], s[16:17], -1
	v_cndmask_b32_e64 v2, 0, 1, s[16:17]
	v_cmp_ne_u32_e64 s[8:9], 1, v2
	s_andn2_b64 vcc, exec, s[16:17]
	s_cbranch_vccnz .LBB0_657
	s_waitcnt vmcnt(10)
	v_cvt_pk_bf16_f32 v2, v70, v94
	ds_write_b32 v168, v2 offset:4352
	v_cvt_pk_bf16_f32 v2, v71, v95
	ds_write_b32 v168, v2 offset:4420
	v_cvt_pk_bf16_f32 v2, v72, v96
	ds_write_b32 v168, v2 offset:4488
	v_cvt_pk_bf16_f32 v2, v73, v97
	ds_write_b32 v168, v2 offset:4556
	s_waitcnt vmcnt(8)
	v_cvt_pk_bf16_f32 v2, v66, v82
	ds_write_b32 v168, v2 offset:4384
	v_cvt_pk_bf16_f32 v2, v67, v83
	ds_write_b32 v168, v2 offset:4452
	v_cvt_pk_bf16_f32 v2, v68, v84
	ds_write_b32 v168, v2 offset:4520
	v_cvt_pk_bf16_f32 v2, v69, v85
	ds_write_b32 v168, v2 offset:4588

; #define PG8_STAGE(bufoff, gbase, voff) do { const char* _gb = (const char*)(gbase); asm volatile("" : "+s"(_gb)); _Pragma("unroll") for (int _i = 0; _i < 2; ++_i) { asm volatile("" : "+v"((voff)[_i])); \
;         __builtin_amdgcn_global_load_lds((const unsigned*)(_gb + (voff)[_i]), (PG8_LAS unsigned*)(lds + (bufoff) + ldsw + _i * 8192), 16, 0, 0); } } while (0)
; #define PG8_LDA(dst, b, h) do { _Pragma("unroll") for (int m = 0; m < 4; ++m) _Pragma("unroll") for (int k = 0; k < 2; ++k) dst[m][k] = *(const PG8_LAS bf16x8*)(lds + PG8_SA(b, h) + aoff + m * 2048 + k * 1024); } while (0)
; #define PG8_LDB(dst, b, h) do { _Pragma("unroll") for (int n = 0; n < 2; ++n) _Pragma("unroll") for (int k = 0; k < 2; ++k) dst[n][k] = *(const PG8_LAS bf16x8*)(lds + PG8_SB(b, h) + boff + n * 2048 + k * 1024); } while (0)
; #define PG8_WAIT_V(n) asm volatile("s_waitcnt vmcnt(" #n ")" ::: "memory")
; #define PG8_WAIT_L(n) asm volatile("s_waitcnt lgkmcnt(" #n ")" ::: "memory")
; #define PG8_BAR __builtin_amdgcn_s_barrier()
; #define PG8_SCHED __builtin_amdgcn_sched_barrier(0)
; #define PG8_STAGE(bufoff, gbase, voff) do { const char* _gb = (const char*)(gbase); asm volatile("" : "+s"(_gb)); _Pragma("unroll") for (int _i = 0; _i < 2; ++_i) { asm volatile("" : "+v"((voff)[_i])); \
;         __builtin_amdgcn_global_load_lds((const unsigned*)(_gb + (voff)[_i]), (PG8_LAS unsigned*)(lds + (bufoff) + ldsw + _i * 8192), 16, 0, 0); } } while (0)
; #define PG8_LDA(dst, b, h) do { _Pragma("unroll") for (int m = 0; m < 4; ++m) _Pragma("unroll") for (int k = 0; k < 2; ++k) dst[m][k] = *(const PG8_LAS bf16x8*)(lds + PG8_SA(b, h) + aoff + m * 2048 + k * 1024); } while (0)
; #define PG8_WAIT_V(n) asm volatile("s_waitcnt vmcnt(" #n ")" ::: "memory")
; template <class Epi, class Sched, bool ALIGN_EPI = false, bool SP2 = false>
; __device__ __forceinline__ void gemm_phase(PG8_LAS unsigned char* lds, const Gemm g, const Sched& S, const Epi& E) {
;     ...
;             PG8_LDB(B0, 0, 0); PG8_LDB(B1, 0, 1); PG8_SCHED; PG8_LDA(At, 0, 0); PG8_STAGE(PG8_SA(1, 1), a1 + hstep, voffA);
;             PG8_WAIT_V(8); PG8_WAIT_L(0); PG8_BAR; PG8_MMA2(0); PG8_BAR; PG8_SCHED;
;             PG8_LDA(At, 0, 1); PG8_STAGE(PG8_SB(0, 0), b2, voffB); PG8_STAGE(PG8_SB(0, 1), b2 + hstep, voffB); PG8_STAGE(PG8_SA(0, 0), a2, voffA);
;             PG8_WAIT_V(8); PG8_WAIT_L(0); PG8_BAR; PG8_MMA2(1); PG8_BAR; PG8_SCHED;
.LBB0_933:
	v_add_u32_e32 v142, s78, v201
	v_add_u32_e32 v147, s79, v201
	s_nop 0
	ds_read_b128 v[6:9], v142
	ds_read_b128 v[62:65], v142 offset:1024
	ds_read_b128 v[138:141], v142 offset:2048
	ds_read_b128 v[142:145], v142 offset:3072
	ds_read_b128 v[164:167], v147
	ds_read_b128 v[168:171], v147 offset:1024
	ds_read_b128 v[172:175], v147 offset:2048
	ds_read_b128 v[176:179], v147 offset:3072
	s_add_u32 s14, s12, 0x100
	s_addc_u32 s15, s13, 0
	s_cmp_eq_u32 s83, 60
	s_cselect_b32 s18, s21, s14
	s_cselect_b32 s19, s20, s15
	s_cselect_b32 s16, s51, s62
	s_cselect_b32 s17, s49, s63
	s_add_u32 s2, s18, 0x80
	s_addc_u32 s3, s19, 0
	s_add_u32 s12, s12, 0x100080
	s_addc_u32 s13, s13, 0
	s_add_i32 m0, s33, 0xc000
	ds_read_b128 v[180:183], v219
	ds_read_b128 v[184:187], v219 offset:1024
	ds_read_b128 v[188:191], v219 offset:2048
	ds_read_b128 v[192:195], v219 offset:3072
	ds_read_b128 v[222:225], v219 offset:4096
	ds_read_b128 v[226:229], v219 offset:5120
	ds_read_b128 v[230:233], v219 offset:6144
	ds_read_b128 v[234:237], v219 offset:7168
	s_nop 0
	global_load_lds_dwordx4 v1, s[12:13]
	s_add_i32 m0, s33, 0xe000
	s_nop 0
	global_load_lds_dwordx4 v199, s[12:13]
	s_waitcnt vmcnt(8)
	s_waitcnt lgkmcnt(0)
	s_barrier
	s_setprio 1
	s_waitcnt lgkmcnt(0)
	v_mfma_f32_16x16x32_bf16 v[118:121], v[6:9], v[180:183], v[118:121]
	v_mfma_f32_16x16x32_bf16 v[114:117], v[138:141], v[180:183], v[114:117]
	v_mfma_f32_16x16x32_bf16 v[106:109], v[6:9], v[188:191], v[106:109]
	v_mfma_f32_16x16x32_bf16 v[86:89], v[138:141], v[188:191], v[86:89]
	v_mfma_f32_16x16x32_bf16 v[134:137], v[6:9], v[222:225], v[134:137]
	v_mfma_f32_16x16x32_bf16 v[90:93], v[138:141], v[222:225], v[90:93]
	v_mfma_f32_16x16x32_bf16 v[130:133], v[6:9], v[230:233], v[130:133]
	v_mfma_f32_16x16x32_bf16 v[110:113], v[138:141], v[230:233], v[110:113]
	v_mfma_f32_16x16x32_bf16 v[94:97], v[164:167], v[180:183], v[94:97]
	v_mfma_f32_16x16x32_bf16 v[82:85], v[172:175], v[180:183], v[82:85]
	v_mfma_f32_16x16x32_bf16 v[78:81], v[164:167], v[188:191], v[78:81]
	v_mfma_f32_16x16x32_bf16 v[74:77], v[172:175], v[188:191], v[74:77]
	v_mfma_f32_16x16x32_bf16 v[126:129], v[164:167], v[222:225], v[126:129]
	v_mfma_f32_16x16x32_bf16 v[98:101], v[172:175], v[222:225], v[98:101]
	v_mfma_f32_16x16x32_bf16 v[122:125], v[164:167], v[230:233], v[122:125]
	v_mfma_f32_16x16x32_bf16 v[102:105], v[172:175], v[230:233], v[102:105]
	v_mfma_f32_16x16x32_bf16 v[118:121], v[62:65], v[184:187], v[118:121]
	v_mfma_f32_16x16x32_bf16 v[114:117], v[142:145], v[184:187], v[114:117]
	v_mfma_f32_16x16x32_bf16 v[106:109], v[62:65], v[192:195], v[106:109]
	v_mfma_f32_16x16x32_bf16 v[86:89], v[142:145], v[192:195], v[86:89]
	v_mfma_f32_16x16x32_bf16 v[134:137], v[62:65], v[226:229], v[134:137]
	v_mfma_f32_16x16x32_bf16 v[90:93], v[142:145], v[226:229], v[90:93]
	v_mfma_f32_16x16x32_bf16 v[130:133], v[62:65], v[234:237], v[130:133]
	v_mfma_f32_16x16x32_bf16 v[110:113], v[142:145], v[234:237], v[110:113]
	v_mfma_f32_16x16x32_bf16 v[94:97], v[168:171], v[184:187], v[94:97]
	v_mfma_f32_16x16x32_bf16 v[82:85], v[176:179], v[184:187], v[82:85]
	v_mfma_f32_16x16x32_bf16 v[78:81], v[168:171], v[192:195], v[78:81]
	v_mfma_f32_16x16x32_bf16 v[74:77], v[176:179], v[192:195], v[74:77]
	v_mfma_f32_16x16x32_bf16 v[126:129], v[168:171], v[226:229], v[126:129]
	v_mfma_f32_16x16x32_bf16 v[98:101], v[176:179], v[226:229], v[98:101]
	v_mfma_f32_16x16x32_bf16 v[122:125], v[168:171], v[234:237], v[122:125]
	v_mfma_f32_16x16x32_bf16 v[102:105], v[176:179], v[234:237], v[102:105]
	s_setprio 0
	s_barrier
	s_add_i32 s84, s78, s25
	s_mov_b64 s[12:13], s[16:17]
	s_mov_b32 m0, s84
	ds_read_b128 v[180:183], v219 offset:16384
	ds_read_b128 v[184:187], v219 offset:17408
	ds_read_b128 v[188:191], v219 offset:18432
	ds_read_b128 v[192:195], v219 offset:19456
	ds_read_b128 v[222:225], v219 offset:20480
	ds_read_b128 v[226:229], v219 offset:21504
	ds_read_b128 v[230:233], v219 offset:22528
	ds_read_b128 v[234:237], v219 offset:23552
	s_nop 0
	global_load_lds_dwordx4 v198, s[12:13]
	s_add_i32 m0, s84, 0x2000
	s_nop 0
	global_load_lds_dwordx4 v200, s[12:13]
	s_add_u32 s12, s16, 0x100000
	s_addc_u32 s13, s17, 0
	s_add_i32 s84, s79, s25
	s_mov_b32 m0, s84
	s_nop 0
	global_load_lds_dwordx4 v198, s[12:13]
	s_add_i32 m0, s84, 0x2000
	s_nop 0
	global_load_lds_dwordx4 v200, s[12:13]
	s_mov_b64 s[12:13], s[18:19]
	s_mov_b32 m0, s33
	s_nop 0
	global_load_lds_dwordx4 v1, s[12:13]
	s_mov_b32 m0, s45
	s_nop 0
	global_load_lds_dwordx4 v199, s[12:13]
	s_waitcnt vmcnt(8)
	s_waitcnt lgkmcnt(0)
	s_barrier
; #define PG8_STAGE(bufoff, gbase, voff) do { const char* _gb = (const char*)(gbase); asm volatile("" : "+s"(_gb)); _Pragma("unroll") for (int _i = 0; _i < 2; ++_i) { asm volatile("" : "+v"((voff)[_i])); \
;         __builtin_amdgcn_global_load_lds((const unsigned*)(_gb + (voff)[_i]), (PG8_LAS unsigned*)(lds + (bufoff) + ldsw + _i * 8192), 16, 0, 0); } } while (0)
; #define PG8_LDA(dst, b, h) do { _Pragma("unroll") for (int m = 0; m < 4; ++m) _Pragma("unroll") for (int k = 0; k < 2; ++k) dst[m][k] = *(const PG8_LAS bf16x8*)(lds + PG8_SA(b, h) + aoff + m * 2048 + k * 1024); } while (0)
; #define PG8_LDB(dst, b, h) do { _Pragma("unroll") for (int n = 0; n < 2; ++n) _Pragma("unroll") for (int k = 0; k < 2; ++k) dst[n][k] = *(const PG8_LAS bf16x8*)(lds + PG8_SB(b, h) + boff + n * 2048 + k * 1024); } while (0)
; #define PG8_WAIT_V(n) asm volatile("s_waitcnt vmcnt(" #n ")" ::: "memory")
; #define PG8_WAIT_L(n) asm volatile("s_waitcnt lgkmcnt(" #n ")" ::: "memory")
; #define PG8_BAR __builtin_amdgcn_s_barrier()
; #define PG8_SCHED __builtin_amdgcn_sched_barrier(0)
; #define PG8_STAGE(bufoff, gbase, voff) do { const char* _gb = (const char*)(gbase); asm volatile("" : "+s"(_gb)); _Pragma("unroll") for (int _i = 0; _i < 2; ++_i) { asm volatile("" : "+v"((voff)[_i])); \
;         __builtin_amdgcn_global_load_lds((const unsigned*)(_gb + (voff)[_i]), (PG8_LAS unsigned*)(lds + (bufoff) + ldsw + _i * 8192), 16, 0, 0); } } while (0)
; #define PG8_LDA(dst, b, h) do { _Pragma("unroll") for (int m = 0; m < 4; ++m) _Pragma("unroll") for (int k = 0; k < 2; ++k) dst[m][k] = *(const PG8_LAS bf16x8*)(lds + PG8_SA(b, h) + aoff + m * 2048 + k * 1024); } while (0)
; #define PG8_LDB(dst, b, h) do { _Pragma("unroll") for (int n = 0; n < 2; ++n) _Pragma("unroll") for (int k = 0; k < 2; ++k) dst[n][k] = *(const PG8_LAS bf16x8*)(lds + PG8_SB(b, h) + boff + n * 2048 + k * 1024); } while (0)
; template <class Epi, class Sched, bool ALIGN_EPI = false, bool SP2 = false>
; __device__ __forceinline__ void gemm_phase(PG8_LAS unsigned char* lds, const Gemm g, const Sched& S, const Epi& E) {
;     ...
;             PG8_WAIT_V(8); PG8_WAIT_L(0); PG8_BAR; PG8_MMA2(1); PG8_BAR; PG8_SCHED;
;             PG8_LDB(B0, 1, 0); PG8_LDB(B1, 1, 1); PG8_SCHED; PG8_LDA(At, 1, 0); PG8_STAGE(PG8_SA(0, 1), a2 + hstep, voffA);
;             PG8_WAIT_V(8); PG8_WAIT_L(0); PG8_BAR; PG8_MMA2(0); PG8_BAR; PG8_SCHED;
	s_setprio 1
	s_waitcnt lgkmcnt(0)
	v_mfma_f32_16x16x32_bf16 v[34:37], v[6:9], v[180:183], v[34:37]
	v_mfma_f32_16x16x32_bf16 v[30:33], v[138:141], v[180:183], v[30:33]
	v_mfma_f32_16x16x32_bf16 v[26:29], v[6:9], v[188:191], v[26:29]
	v_mfma_f32_16x16x32_bf16 v[22:25], v[138:141], v[188:191], v[22:25]
	v_mfma_f32_16x16x32_bf16 v[70:73], v[6:9], v[222:225], v[70:73]
	v_mfma_f32_16x16x32_bf16 v[66:69], v[138:141], v[222:225], v[66:69]
	v_mfma_f32_16x16x32_bf16 v[50:53], v[138:141], v[230:233], v[50:53]
	v_mfma_f32_16x16x32_bf16 v[18:21], v[164:167], v[180:183], v[18:21]
	v_mfma_f32_16x16x32_bf16 v[14:17], v[172:175], v[180:183], v[14:17]
	v_mfma_f32_16x16x32_bf16 v[10:13], v[164:167], v[188:191], v[10:13]
	v_mfma_f32_16x16x32_bf16 v[2:5], v[172:175], v[188:191], v[2:5]
	v_mfma_f32_16x16x32_bf16 v[54:57], v[164:167], v[222:225], v[54:57]
	v_mfma_f32_16x16x32_bf16 v[46:49], v[172:175], v[222:225], v[46:49]
	v_mfma_f32_16x16x32_bf16 v[42:45], v[164:167], v[230:233], v[42:45]
	v_mfma_f32_16x16x32_bf16 v[38:41], v[172:175], v[230:233], v[38:41]
	v_mfma_f32_16x16x32_bf16 v[34:37], v[62:65], v[184:187], v[34:37]
	v_mfma_f32_16x16x32_bf16 v[30:33], v[142:145], v[184:187], v[30:33]
	v_mfma_f32_16x16x32_bf16 v[26:29], v[62:65], v[192:195], v[26:29]
	v_mfma_f32_16x16x32_bf16 v[22:25], v[142:145], v[192:195], v[22:25]
	v_mfma_f32_16x16x32_bf16 v[70:73], v[62:65], v[226:229], v[70:73]
	v_mfma_f32_16x16x32_bf16 v[66:69], v[142:145], v[226:229], v[66:69]
	v_mfma_f32_16x16x32_bf16 v[6:9], v[6:9], v[230:233], v[58:61]
	v_mfma_f32_16x16x32_bf16 v[50:53], v[142:145], v[234:237], v[50:53]
	v_mfma_f32_16x16x32_bf16 v[18:21], v[168:171], v[184:187], v[18:21]
	v_mfma_f32_16x16x32_bf16 v[14:17], v[176:179], v[184:187], v[14:17]
	v_mfma_f32_16x16x32_bf16 v[10:13], v[168:171], v[192:195], v[10:13]
	v_mfma_f32_16x16x32_bf16 v[2:5], v[176:179], v[192:195], v[2:5]
	v_mfma_f32_16x16x32_bf16 v[54:57], v[168:171], v[226:229], v[54:57]
	v_mfma_f32_16x16x32_bf16 v[46:49], v[176:179], v[226:229], v[46:49]
	v_mfma_f32_16x16x32_bf16 v[42:45], v[168:171], v[234:237], v[42:45]
	v_mfma_f32_16x16x32_bf16 v[38:41], v[176:179], v[234:237], v[38:41]
	v_mfma_f32_16x16x32_bf16 v[6:9], v[62:65], v[234:237], v[6:9]
	s_setprio 0
	s_barrier
	s_add_i32 s84, 0, 0x18000
	s_add_i32 s85, 0, 0x1c000
	v_add_u32_e32 v142, s84, v201
	v_add_u32_e32 v147, s85, v201
	ds_read_b128 v[58:61], v142
	ds_read_b128 v[62:65], v142 offset:1024
	ds_read_b128 v[138:141], v142 offset:2048
	ds_read_b128 v[142:145], v142 offset:3072
	ds_read_b128 v[164:167], v147
	ds_read_b128 v[168:171], v147 offset:1024
	ds_read_b128 v[172:175], v147 offset:2048
	ds_read_b128 v[176:179], v147 offset:3072
	s_add_u32 s12, s18, 0x100000
	s_addc_u32 s13, s19, 0
	s_mov_b32 m0, s47
	ds_read_b128 v[180:183], v219 offset:32768
	ds_read_b128 v[184:187], v219 offset:33792
	ds_read_b128 v[188:191], v219 offset:34816
	ds_read_b128 v[192:195], v219 offset:35840
	ds_read_b128 v[222:225], v219 offset:36864
	ds_read_b128 v[226:229], v219 offset:37888
	ds_read_b128 v[230:233], v219 offset:38912
	ds_read_b128 v[234:237], v219 offset:39936
	s_nop 0
	global_load_lds_dwordx4 v1, s[12:13]
	s_mov_b32 m0, s87
	s_nop 0
	global_load_lds_dwordx4 v199, s[12:13]
	s_waitcnt vmcnt(8)
	s_waitcnt lgkmcnt(0)
	s_barrier
	s_setprio 1
	s_waitcnt lgkmcnt(0)
	v_mfma_f32_16x16x32_bf16 v[118:121], v[58:61], v[180:183], v[118:121]
	v_mfma_f32_16x16x32_bf16 v[114:117], v[138:141], v[180:183], v[114:117]
	v_mfma_f32_16x16x32_bf16 v[106:109], v[58:61], v[188:191], v[106:109]
	v_mfma_f32_16x16x32_bf16 v[86:89], v[138:141], v[188:191], v[86:89]
	v_mfma_f32_16x16x32_bf16 v[134:137], v[58:61], v[222:225], v[134:137]
	v_mfma_f32_16x16x32_bf16 v[90:93], v[138:141], v[222:225], v[90:93]
	v_mfma_f32_16x16x32_bf16 v[130:133], v[58:61], v[230:233], v[130:133]
	v_mfma_f32_16x16x32_bf16 v[110:113], v[138:141], v[230:233], v[110:113]
	v_mfma_f32_16x16x32_bf16 v[94:97], v[164:167], v[180:183], v[94:97]
	v_mfma_f32_16x16x32_bf16 v[82:85], v[172:175], v[180:183], v[82:85]
	v_mfma_f32_16x16x32_bf16 v[78:81], v[164:167], v[188:191], v[78:81]
	v_mfma_f32_16x16x32_bf16 v[74:77], v[172:175], v[188:191], v[74:77]
	v_mfma_f32_16x16x32_bf16 v[126:129], v[164:167], v[222:225], v[126:129]
	v_mfma_f32_16x16x32_bf16 v[98:101], v[172:175], v[222:225], v[98:101]
	v_mfma_f32_16x16x32_bf16 v[122:125], v[164:167], v[230:233], v[122:125]
	v_mfma_f32_16x16x32_bf16 v[102:105], v[172:175], v[230:233], v[102:105]
	v_mfma_f32_16x16x32_bf16 v[118:121], v[62:65], v[184:187], v[118:121]
	v_mfma_f32_16x16x32_bf16 v[114:117], v[142:145], v[184:187], v[114:117]
	v_mfma_f32_16x16x32_bf16 v[106:109], v[62:65], v[192:195], v[106:109]
	v_mfma_f32_16x16x32_bf16 v[86:89], v[142:145], v[192:195], v[86:89]
	v_mfma_f32_16x16x32_bf16 v[134:137], v[62:65], v[226:229], v[134:137]
	v_mfma_f32_16x16x32_bf16 v[90:93], v[142:145], v[226:229], v[90:93]
	v_mfma_f32_16x16x32_bf16 v[130:133], v[62:65], v[234:237], v[130:133]
	v_mfma_f32_16x16x32_bf16 v[110:113], v[142:145], v[234:237], v[110:113]
	v_mfma_f32_16x16x32_bf16 v[94:97], v[168:171], v[184:187], v[94:97]
	v_mfma_f32_16x16x32_bf16 v[82:85], v[176:179], v[184:187], v[82:85]
	v_mfma_f32_16x16x32_bf16 v[78:81], v[168:171], v[192:195], v[78:81]
	v_mfma_f32_16x16x32_bf16 v[74:77], v[176:179], v[192:195], v[74:77]
	v_mfma_f32_16x16x32_bf16 v[126:129], v[168:171], v[226:229], v[126:129]
	v_mfma_f32_16x16x32_bf16 v[98:101], v[176:179], v[226:229], v[98:101]
	v_mfma_f32_16x16x32_bf16 v[122:125], v[168:171], v[234:237], v[122:125]
	v_mfma_f32_16x16x32_bf16 v[102:105], v[176:179], v[234:237], v[102:105]
	s_setprio 0
	s_barrier
; #define PG8_STAGE(bufoff, gbase, voff) do { const char* _gb = (const char*)(gbase); asm volatile("" : "+s"(_gb)); _Pragma("unroll") for (int _i = 0; _i < 2; ++_i) { asm volatile("" : "+v"((voff)[_i])); \
;         __builtin_amdgcn_global_load_lds((const unsigned*)(_gb + (voff)[_i]), (PG8_LAS unsigned*)(lds + (bufoff) + ldsw + _i * 8192), 16, 0, 0); } } while (0)
; #define PG8_LDA(dst, b, h) do { _Pragma("unroll") for (int m = 0; m < 4; ++m) _Pragma("unroll") for (int k = 0; k < 2; ++k) dst[m][k] = *(const PG8_LAS bf16x8*)(lds + PG8_SA(b, h) + aoff + m * 2048 + k * 1024); } while (0)
; #define PG8_LDB(dst, b, h) do { _Pragma("unroll") for (int n = 0; n < 2; ++n) _Pragma("unroll") for (int k = 0; k < 2; ++k) dst[n][k] = *(const PG8_LAS bf16x8*)(lds + PG8_SB(b, h) + boff + n * 2048 + k * 1024); } while (0)
; #define PG8_WAIT_V(n) asm volatile("s_waitcnt vmcnt(" #n ")" ::: "memory")
; #define PG8_WAIT_L(n) asm volatile("s_waitcnt lgkmcnt(" #n ")" ::: "memory")
; #define PG8_BAR __builtin_amdgcn_s_barrier()
; #define PG8_SCHED __builtin_amdgcn_sched_barrier(0)
; #define PG8_STAGE(bufoff, gbase, voff) do { const char* _gb = (const char*)(gbase); asm volatile("" : "+s"(_gb)); _Pragma("unroll") for (int _i = 0; _i < 2; ++_i) { asm volatile("" : "+v"((voff)[_i])); \
;         __builtin_amdgcn_global_load_lds((const unsigned*)(_gb + (voff)[_i]), (PG8_LAS unsigned*)(lds + (bufoff) + ldsw + _i * 8192), 16, 0, 0); } } while (0)
; #define PG8_LDA(dst, b, h) do { _Pragma("unroll") for (int m = 0; m < 4; ++m) _Pragma("unroll") for (int k = 0; k < 2; ++k) dst[m][k] = *(const PG8_LAS bf16x8*)(lds + PG8_SA(b, h) + aoff + m * 2048 + k * 1024); } while (0)
; #define PG8_WAIT_V(n) asm volatile("s_waitcnt vmcnt(" #n ")" ::: "memory")
; template <class Epi, class Sched, bool ALIGN_EPI = false, bool SP2 = false>
; __device__ __forceinline__ void gemm_phase(PG8_LAS unsigned char* lds, const Gemm g, const Sched& S, const Epi& E) {
;     ...
;             PG8_LDB(B0, 1, 0); PG8_LDB(B1, 1, 1); PG8_SCHED; PG8_LDA(At, 1, 0); PG8_STAGE(PG8_SA(0, 1), a2 + hstep, voffA);
;             PG8_WAIT_V(8); PG8_WAIT_L(0); PG8_BAR; PG8_MMA2(0); PG8_BAR; PG8_SCHED;
;             PG8_LDA(At, 1, 1); PG8_STAGE(PG8_SB(1, 0), b3, voffB); PG8_STAGE(PG8_SB(1, 1), b3 + hstep, voffB); PG8_STAGE(PG8_SA(1, 0), a3, voffA);
;             PG8_WAIT_V(8); PG8_WAIT_L(0); PG8_BAR; PG8_MMA2(1); PG8_BAR; PG8_SCHED;
	s_add_u32 s12, s16, 0x80
	s_addc_u32 s13, s17, 0
	s_add_i32 s18, s84, s25
	s_mov_b32 m0, s18
	ds_read_b128 v[180:183], v219 offset:49152
	ds_read_b128 v[184:187], v219 offset:50176
	ds_read_b128 v[188:191], v219 offset:51200
	ds_read_b128 v[192:195], v219 offset:52224
	ds_read_b128 v[222:225], v219 offset:53248
	ds_read_b128 v[226:229], v219 offset:54272
	ds_read_b128 v[230:233], v219 offset:55296
	ds_read_b128 v[234:237], v219 offset:56320
	s_nop 0
	global_load_lds_dwordx4 v198, s[12:13]
	s_add_i32 m0, s18, 0x2000
	s_nop 0
	global_load_lds_dwordx4 v200, s[12:13]
	s_add_u32 s12, s16, 0x100080
	s_addc_u32 s13, s17, 0
	s_add_i32 s16, s85, s25
	s_mov_b32 m0, s16
	s_nop 0
	global_load_lds_dwordx4 v198, s[12:13]
	s_add_i32 m0, s16, 0x2000
	s_nop 0
	global_load_lds_dwordx4 v200, s[12:13]
	s_mov_b32 m0, s71
	s_nop 0
	global_load_lds_dwordx4 v1, s[2:3]
	s_mov_b32 m0, s72
	s_nop 0
	global_load_lds_dwordx4 v199, s[2:3]
	s_waitcnt vmcnt(8)
	s_waitcnt lgkmcnt(0)
	s_barrier
	s_setprio 1
	s_waitcnt lgkmcnt(0)
	v_mfma_f32_16x16x32_bf16 v[6:9], v[58:61], v[230:233], v[6:9]
	v_mfma_f32_16x16x32_bf16 v[34:37], v[58:61], v[180:183], v[34:37]
	v_mfma_f32_16x16x32_bf16 v[26:29], v[58:61], v[188:191], v[26:29]
	v_mfma_f32_16x16x32_bf16 v[70:73], v[58:61], v[222:225], v[70:73]
	v_mfma_f32_16x16x32_bf16 v[58:61], v[62:65], v[234:237], v[6:9]
	v_mfma_f32_16x16x32_bf16 v[6:9], v[138:141], v[230:233], v[50:53]
	v_mfma_f32_16x16x32_bf16 v[50:53], v[142:145], v[234:237], v[6:9]
	v_mfma_f32_16x16x32_bf16 v[6:9], v[164:167], v[180:183], v[18:21]
	v_mfma_f32_16x16x32_bf16 v[18:21], v[168:171], v[184:187], v[6:9]
	v_mfma_f32_16x16x32_bf16 v[6:9], v[172:175], v[180:183], v[14:17]
	v_mfma_f32_16x16x32_bf16 v[14:17], v[176:179], v[184:187], v[6:9]
	v_mfma_f32_16x16x32_bf16 v[6:9], v[164:167], v[188:191], v[10:13]
	v_mfma_f32_16x16x32_bf16 v[10:13], v[168:171], v[192:195], v[6:9]
	v_mfma_f32_16x16x32_bf16 v[6:9], v[164:167], v[222:225], v[54:57]
	v_mfma_f32_16x16x32_bf16 v[54:57], v[168:171], v[226:229], v[6:9]
	v_mfma_f32_16x16x32_bf16 v[6:9], v[172:175], v[222:225], v[46:49]
	v_mfma_f32_16x16x32_bf16 v[46:49], v[176:179], v[226:229], v[6:9]
	v_mfma_f32_16x16x32_bf16 v[6:9], v[164:167], v[230:233], v[42:45]
	v_mfma_f32_16x16x32_bf16 v[30:33], v[138:141], v[180:183], v[30:33]
	v_mfma_f32_16x16x32_bf16 v[22:25], v[138:141], v[188:191], v[22:25]
	v_mfma_f32_16x16x32_bf16 v[66:69], v[138:141], v[222:225], v[66:69]
	v_mfma_f32_16x16x32_bf16 v[2:5], v[172:175], v[188:191], v[2:5]
	v_mfma_f32_16x16x32_bf16 v[42:45], v[168:171], v[234:237], v[6:9]
	v_mfma_f32_16x16x32_bf16 v[6:9], v[172:175], v[230:233], v[38:41]
	v_mfma_f32_16x16x32_bf16 v[34:37], v[62:65], v[184:187], v[34:37]
	v_mfma_f32_16x16x32_bf16 v[30:33], v[142:145], v[184:187], v[30:33]
	v_mfma_f32_16x16x32_bf16 v[26:29], v[62:65], v[192:195], v[26:29]
	v_mfma_f32_16x16x32_bf16 v[22:25], v[142:145], v[192:195], v[22:25]
	v_mfma_f32_16x16x32_bf16 v[70:73], v[62:65], v[226:229], v[70:73]
	v_mfma_f32_16x16x32_bf16 v[66:69], v[142:145], v[226:229], v[66:69]
	v_mfma_f32_16x16x32_bf16 v[2:5], v[176:179], v[192:195], v[2:5]
	v_mfma_f32_16x16x32_bf16 v[38:41], v[176:179], v[234:237], v[6:9]
	s_setprio 0
	s_barrier
	s_add_i32 s83, s83, 2
	s_add_u32 s62, s62, 0x100
	s_addc_u32 s63, s63, 0
	s_cmp_gt_u32 s83, 61
	s_mov_b64 s[12:13], s[14:15]
	s_cbranch_scc0 .LBB0_933
	s_and_b64 vcc, exec, s[38:39]
	s_cbranch_vccz .LBB0_936
	s_barrier

; __global__ void __launch_bounds__(NWAVES * 64, 2) hyb_fwd(Args args) {
	.amdhsa_kernel _Z7hyb_fwd4Args
		.amdhsa_group_segment_fixed_size 0
		.amdhsa_private_segment_fixed_size 0
		.amdhsa_kernarg_size 464
		.amdhsa_user_sgpr_count 2
		.amdhsa_user_sgpr_dispatch_ptr 0
		.amdhsa_user_sgpr_queue_ptr 0
		.amdhsa_user_sgpr_kernarg_segment_ptr 1
		.amdhsa_user_sgpr_dispatch_id 0
		.amdhsa_user_sgpr_kernarg_preload_length 0
		.amdhsa_user_sgpr_kernarg_preload_offset 0
		.amdhsa_user_sgpr_private_segment_size 0
		.amdhsa_uses_dynamic_stack 0
		.amdhsa_enable_private_segment 0
		.amdhsa_system_sgpr_workgroup_id_x 1
		.amdhsa_system_sgpr_workgroup_id_y 0
		.amdhsa_system_sgpr_workgroup_id_z 0
		.amdhsa_system_sgpr_workgroup_info 0
		.amdhsa_system_vgpr_workitem_id 0
		.amdhsa_next_free_vgpr 239
		.amdhsa_next_free_sgpr 98
		.amdhsa_accum_offset 240
		.amdhsa_reserve_vcc 1
		.amdhsa_float_round_mode_32 0
		.amdhsa_float_round_mode_16_64 0
		.amdhsa_float_denorm_mode_32 3
		.amdhsa_float_denorm_mode_16_64 3
		.amdhsa_dx10_clamp 1
		.amdhsa_ieee_mode 1
		.amdhsa_fp16_overflow 0
		.amdhsa_tg_split 0
		.amdhsa_exception_fp_ieee_invalid_op 0
		.amdhsa_exception_fp_denorm_src 0
		.amdhsa_exception_fp_ieee_div_zero 0
		.amdhsa_exception_fp_ieee_overflow 0
		.amdhsa_exception_fp_ieee_underflow 0
		.amdhsa_exception_fp_ieee_inexact 0
		.amdhsa_exception_int_div_zero 0
	.end_amdhsa_kernel

; __global__ void __launch_bounds__(NWAVES * 64, 2) hyb_fwd(Args args) {
amdhsa.kernels:
  - .agpr_count:     0
    .args:
      - .offset:         0
        .size:           208
        .value_kind:     by_value
      - .offset:         208
        .size:           4
        .value_kind:     hidden_block_count_x
      - .offset:         212
        .size:           4
        .value_kind:     hidden_block_count_y
      - .offset:         216
        .size:           4
        .value_kind:     hidden_block_count_z
      - .offset:         220
        .size:           2
        .value_kind:     hidden_group_size_x
      - .offset:         222
        .size:           2
        .value_kind:     hidden_group_size_y
      - .offset:         224
        .size:           2
        .value_kind:     hidden_group_size_z
      - .offset:         226
        .size:           2
        .value_kind:     hidden_remainder_x
      - .offset:         228
        .size:           2
        .value_kind:     hidden_remainder_y
      - .offset:         230
        .size:           2
        .value_kind:     hidden_remainder_z
      - .offset:         248
        .size:           8
        .value_kind:     hidden_global_offset_x
      - .offset:         256
        .size:           8
        .value_kind:     hidden_global_offset_y
      - .offset:         264
        .size:           8
        .value_kind:     hidden_global_offset_z
      - .offset:         272
        .size:           2
        .value_kind:     hidden_grid_dims
      - .offset:         328
        .size:           4
        .value_kind:     hidden_dynamic_lds_size
    .group_segment_fixed_size: 0
    .kernarg_segment_align: 8
    .kernarg_segment_size: 464
    .language:       OpenCL C
    .language_version:
      - 2
      - 0
    .max_flat_workgroup_size: 512
    .name:           _Z7hyb_fwd4Args
    .private_segment_fixed_size: 0
    .sgpr_count:     104
    .sgpr_spill_count: 55
    .symbol:         _Z7hyb_fwd4Args.kd
    .uniform_work_group_size: 1
    .uses_dynamic_stack: false
    .vgpr_count:     239
    .vgpr_spill_count: 0
    .wavefront_size: 64
